# xqk2
# speedup vs baseline: 1.0010x; 1.0010x over previous
; __device__ __forceinline__ void xattn_item(const Params& p, char* smem, const int tile, const int hm) {
;     ...
;     const int tok0 = tile * 64;
;     const int b = tok0 >> 13;
;     __syncthreads();
; #pragma unroll
;     for (int i = 0; i < 8; ++i) {
;       const int c = tid + 256 * i, row = c >> 5, cc = c & 31;
;       *(uint4*)(sQ + row * 264 + cc * 8) = *(const uint4*)(qm + (size_t)(tok0 + row) * 1024 + hm * 256 + cc * 8);
;     }
;     f32x4 acc[4][4];
;     u32x4 st[8];
; #pragma unroll
;     for (int m = 0; m < 4; ++m)
; #pragma unroll
;       for (int n = 0; n < 4; ++n) acc[m][n] = f32x4{0.f, 0.f, 0.f, 0.f};
;     for (int kt = 0; kt < 4; ++kt) {
; #pragma unroll
;       for (int i = 0; i < 8; ++i) {
;         const int c = tid + 256 * i, row = c >> 3, cc = c & 7;
;         st[i] = *(const u32x4*)(kmem + (size_t)(b * 256 + row) * 1024 + hm * 256 + kt * 64 + cc * 8);
;       }
;       __syncthreads();
; #pragma unroll
;       for (int i = 0; i < 8; ++i) {
;         const int c = tid + 256 * i, row = c >> 3, cc = c & 7;
;         *(u32x4*)(sT + row * 72 + cc * 8) = st[i];
;       }
;       __syncthreads();
.LBB0_366:
	s_and_b64 vcc, exec, s[4:5]
	s_cbranch_vccz .LBB0_432
	s_lshl_b32 s4, s93, 1
	s_lshr_b32 s5, s94, 2
	s_add_i32 s42, s4, s5
	s_lshl_b32 s4, s94, 8
	s_and_b32 s41, s4, 0x300
	v_mov_b32_e32 v16, v197
	s_lshl_b32 s6, s42, 6
	s_lshl_b32 s40, s41, 1
	s_add_u32 s4, s12, s40
	v_lshlrev_b32_e32 v0, 4, v16
	v_add_u32_e32 v7, 0x100, v16
	s_addc_u32 s5, s13, 0
	v_and_b32_e32 v100, 0x1f0, v0
	v_ashrrev_i32_e32 v4, 5, v16
	v_ashrrev_i32_e32 v8, 5, v7
	v_lshl_add_u64 v[0:1], s[4:5], 0, v[100:101]
	v_add_u32_e32 v2, s6, v4
	s_waitcnt vmcnt(20)
	v_mad_u64_u32 v[62:63], s[4:5], v4, s81, v[100:101]
	v_add_u32_e32 v4, s6, v8
	v_ashrrev_i32_e32 v3, 31, v2
	v_ashrrev_i32_e32 v5, 31, v4
	v_lshlrev_b64 v[2:3], 11, v[2:3]
	v_lshlrev_b64 v[4:5], 11, v[4:5]
	v_lshl_add_u64 v[2:3], v[0:1], 0, v[2:3]
	v_lshl_add_u64 v[4:5], v[0:1], 0, v[4:5]
	s_waitcnt vmcnt(19)
	v_mad_u64_u32 v[64:65], s[4:5], v8, s81, v[100:101]
	v_add_u32_e32 v8, 0x200, v16
	v_add_u32_e32 v9, 0x300, v16
	s_barrier
	global_load_dwordx4 v[18:21], v[2:3], off
	global_load_dwordx4 v[22:25], v[4:5], off
	v_ashrrev_i32_e32 v4, 5, v8
	v_ashrrev_i32_e32 v10, 5, v9
	v_add_u32_e32 v2, s6, v4
	v_mad_u64_u32 v[94:95], s[4:5], v4, s81, v[100:101]
	v_add_u32_e32 v4, s6, v10
	v_ashrrev_i32_e32 v3, 31, v2
	v_ashrrev_i32_e32 v5, 31, v4
	v_lshlrev_b64 v[2:3], 11, v[2:3]
	v_lshlrev_b64 v[4:5], 11, v[4:5]
	v_lshl_add_u64 v[2:3], v[0:1], 0, v[2:3]
	v_lshl_add_u64 v[4:5], v[0:1], 0, v[4:5]
	v_mad_u64_u32 v[96:97], s[4:5], v10, s81, v[100:101]
	v_add_u32_e32 v10, 0x400, v16
	v_add_u32_e32 v11, 0x500, v16
	global_load_dwordx4 v[26:29], v[2:3], off
	global_load_dwordx4 v[30:33], v[4:5], off
	v_ashrrev_i32_e32 v4, 5, v10
	v_ashrrev_i32_e32 v12, 5, v11
	v_add_u32_e32 v2, s6, v4
	v_mad_u64_u32 v[98:99], s[4:5], v4, s81, v[100:101]
	v_add_u32_e32 v4, s6, v12
	v_ashrrev_i32_e32 v3, 31, v2
	v_ashrrev_i32_e32 v5, 31, v4
	v_lshlrev_b64 v[2:3], 11, v[2:3]
	v_lshlrev_b64 v[4:5], 11, v[4:5]
	v_lshl_add_u64 v[2:3], v[0:1], 0, v[2:3]
	v_lshl_add_u64 v[4:5], v[0:1], 0, v[4:5]
	v_mad_u64_u32 v[104:105], s[4:5], v12, s81, v[100:101]
	v_add_u32_e32 v12, 0x600, v16
	global_load_dwordx4 v[34:37], v[2:3], off
	global_load_dwordx4 v[38:41], v[4:5], off
	v_ashrrev_i32_e32 v4, 5, v12
	v_add_u32_e32 v17, 0x700, v16
	v_add_u32_e32 v2, s6, v4
	v_ashrrev_i32_e32 v13, 5, v17
	v_ashrrev_i32_e32 v3, 31, v2
	v_mad_u64_u32 v[106:107], s[4:5], v4, s81, v[100:101]
	v_add_u32_e32 v4, s6, v13
	v_lshlrev_b64 v[2:3], 11, v[2:3]
	v_ashrrev_i32_e32 v5, 31, v4
	v_lshl_add_u64 v[2:3], v[0:1], 0, v[2:3]
	v_lshlrev_b64 v[4:5], 11, v[4:5]
	v_lshl_add_u64 v[0:1], v[0:1], 0, v[4:5]
	global_load_dwordx4 v[42:45], v[2:3], off
	global_load_dwordx4 v[46:49], v[0:1], off
	v_lshlrev_b32_e32 v6, 3, v16
	s_ashr_i32 s42, s42, 7
	v_mad_u64_u32 v[108:109], s[4:5], v13, s81, v[100:101]
	s_lshl_b32 s43, s42, 8
	v_and_b32_e32 v0, 56, v6
	v_ashrrev_i32_e32 v65, 3, v16
	v_ashrrev_i32_e32 v66, 3, v7
	v_ashrrev_i32_e32 v67, 3, v8
	s_waitcnt vmcnt(26)
	v_ashrrev_i32_e32 v68, 3, v9
	v_ashrrev_i32_e32 v69, 3, v10
	v_ashrrev_i32_e32 v70, 3, v11
	v_ashrrev_i32_e32 v71, 3, v12
	v_ashrrev_i32_e32 v72, 3, v17
	s_add_u32 s4, s52, s40
	v_lshlrev_b32_e32 v100, 1, v0
	v_add_u32_e32 v0, s43, v65
	v_add_u32_e32 v2, s43, v66
	v_add_u32_e32 v4, s43, v67
	v_add_u32_e32 v6, s43, v68
	v_add_u32_e32 v8, s43, v69
	v_add_u32_e32 v10, s43, v70
	v_add_u32_e32 v12, s43, v71
	v_add_u32_e32 v90, s43, v72
	s_addc_u32 s5, s53, 0
	v_ashrrev_i32_e32 v1, 31, v0
	v_ashrrev_i32_e32 v3, 31, v2
	v_ashrrev_i32_e32 v5, 31, v4
	v_ashrrev_i32_e32 v7, 31, v6
	v_ashrrev_i32_e32 v9, 31, v8
	v_ashrrev_i32_e32 v11, 31, v10
	v_ashrrev_i32_e32 v13, 31, v12
	v_ashrrev_i32_e32 v91, 31, v90
	v_lshl_add_u64 v[14:15], s[4:5], 0, v[100:101]
	v_lshlrev_b64 v[0:1], 11, v[0:1]
	v_lshlrev_b64 v[2:3], 11, v[2:3]
	v_lshlrev_b64 v[4:5], 11, v[4:5]
	v_lshlrev_b64 v[6:7], 11, v[6:7]
	v_lshlrev_b64 v[8:9], 11, v[8:9]
	v_lshlrev_b64 v[10:11], 11, v[10:11]
	v_lshlrev_b64 v[12:13], 11, v[12:13]
	v_lshlrev_b64 v[90:91], 11, v[90:91]
	v_lshl_add_u64 v[0:1], v[14:15], 0, v[0:1]
	v_lshl_add_u64 v[2:3], v[14:15], 0, v[2:3]
	v_lshl_add_u64 v[4:5], v[14:15], 0, v[4:5]
	v_lshl_add_u64 v[6:7], v[14:15], 0, v[6:7]
	v_lshl_add_u64 v[8:9], v[14:15], 0, v[8:9]
	v_lshl_add_u64 v[10:11], v[14:15], 0, v[10:11]
	v_lshl_add_u64 v[12:13], v[14:15], 0, v[12:13]
	v_lshl_add_u64 v[14:15], v[14:15], 0, v[90:91]
	v_lshrrev_b32_e32 v254, 6, v197
	v_and_b32_e32 v255, 15, v197
	v_lshl_add_u32 v254, v254, 6, v255
	v_bfe_u32 v255, v197, 4, 2
	v_lshlrev_b32_e32 v254, 11, v254
	v_lshl_add_u32 v252, v255, 4, v254
	v_add_u32_e32 v253, 0x10000, v252
	s_lshl_b32 s100, s43, 11
	s_add_u32 s96, s52, s40
	s_addc_u32 s97, s53, 0
	s_add_u32 s96, s96, s100
	s_addc_u32 s97, s97, 0
	s_add_u32 s98, s96, 0x8000
	s_addc_u32 s99, s97, 0
	global_load_dwordx4 v[210:213], v252, s[96:97]
	global_load_dwordx4 v[214:217], v252, s[96:97] offset:64
	global_load_dwordx4 v[218:221], v252, s[98:99]
	global_load_dwordx4 v[222:225], v252, s[98:99] offset:64
	global_load_dwordx4 v[226:229], v253, s[96:97]
	global_load_dwordx4 v[230:233], v253, s[96:97] offset:64
	global_load_dwordx4 v[234:237], v253, s[98:99]
	global_load_dwordx4 v[238:241], v253, s[98:99] offset:64
	global_load_dwordx4 v[74:77], v252, s[96:97] offset:128
	global_load_dwordx4 v[78:81], v252, s[96:97] offset:192
	global_load_dwordx4 v[82:85], v252, s[98:99] offset:128
	global_load_dwordx4 v[86:89], v252, s[98:99] offset:192
	global_load_dwordx4 v[90:93], v253, s[96:97] offset:128
	global_load_dwordx4 v[114:117], v253, s[96:97] offset:192
	global_load_dwordx4 v[172:175], v253, s[98:99] offset:128
	global_load_dwordx4 v[176:179], v253, s[98:99] offset:192
	v_mul_lo_u32 v17, v65, s82
	s_waitcnt vmcnt(23)
	ds_write_b128 v62, v[18:21]
	s_waitcnt vmcnt(22)
	ds_write_b128 v64, v[22:25]
	s_waitcnt vmcnt(21)
	ds_write_b128 v94, v[26:29]
	s_waitcnt vmcnt(20)
	ds_write_b128 v96, v[30:33]
	s_waitcnt vmcnt(19)
	ds_write_b128 v98, v[34:37]
	s_waitcnt vmcnt(18)
	ds_write_b128 v104, v[38:41]
	s_waitcnt vmcnt(17)
	ds_write_b128 v106, v[42:45]
	s_waitcnt vmcnt(16)
	ds_write_b128 v108, v[46:49]
	v_add_u32_e32 v98, v100, v17
	v_mul_lo_u32 v17, v66, s82
	v_add_u32_e32 v99, v100, v17
	v_mul_lo_u32 v17, v67, s82
	v_add_u32_e32 v104, v100, v17
	v_mul_lo_u32 v17, v68, s82
	v_add_u32_e32 v105, v100, v17
	v_mul_lo_u32 v17, v69, s82
	v_add_u32_e32 v106, v100, v17
	v_mul_lo_u32 v17, v70, s82
	v_bfe_u32 v73, v16, 4, 2
	v_add_u32_e32 v108, v100, v17
	v_mul_lo_u32 v17, v71, s82
	v_and_b32_e32 v112, 15, v16
	v_lshlrev_b32_e32 v64, 4, v73
	v_add_u32_e32 v109, v100, v17
	v_mul_lo_u32 v17, v72, s82
	v_add_u32_e32 v110, v100, v17
	v_mad_u32_u24 v17, v112, s81, v64
	s_waitcnt lgkmcnt(0)
	s_barrier
; #define MFMA(a, b, c) __builtin_amdgcn_mfma_f32_16x16x32_bf16((a), (b), (c), 0, 0, 0)
; __device__ __forceinline__ void xattn_item(const Params& p, char* smem, const int tile, const int hm) {
;     ...
; #pragma unroll
;       for (int ks = 0; ks < 2; ++ks) {
;         bf16x8 af[4], bfr[4];
; #pragma unroll
;         for (int m = 0; m < 4; ++m) af[m] = *(const bf16x8*)(sQ + (m * 16 + l15) * 264 + kt * 64 + ks * 32 + lq * 8);
; #pragma unroll
;         for (int n = 0; n < 4; ++n) bfr[n] = *(const bf16x8*)(sT + (w * 64 + n * 16 + l15) * 72 + ks * 32 + lq * 8);
; #pragma unroll
;         for (int m = 0; m < 4; ++m)
; #pragma unroll
;           for (int n = 0; n < 4; ++n) acc[m][n] = MFMA(af[m], bfr[n], acc[m][n]);
;       }
	v_and_b32_e32 v22, 0xfffffcf, v16
	v_mul_lo_u32 v22, v22, s82
	v_add_u32_e32 v107, v64, v22
	v_cmp_eq_u32_e32 vcc, 0, v112
	v_or_b32_e32 v54, 48, v16
	v_mul_lo_u32 v54, v54, s82
	v_add_u32_e32 v111, v64, v54
	ds_read_b128 v[140:143], v17
	ds_read_b128 v[144:147], v17 offset:8448
	ds_read_b128 v[148:151], v17 offset:16896
	ds_read_b128 v[152:155], v17 offset:25344
	ds_read_b128 v[156:159], v17 offset:64
	ds_read_b128 v[160:163], v17 offset:8512
	ds_read_b128 v[164:167], v17 offset:16960
	ds_read_b128 v[168:171], v17 offset:25408
	s_waitcnt vmcnt(8)
	s_waitcnt lgkmcnt(4)
	v_mfma_f32_16x16x32_bf16 v[60:63], v[140:143], v[210:213], 0
	v_mfma_f32_16x16x32_bf16 v[56:59], v[140:143], v[218:221], 0
	v_mfma_f32_16x16x32_bf16 v[52:55], v[140:143], v[226:229], 0
	v_mfma_f32_16x16x32_bf16 v[48:51], v[140:143], v[234:237], 0
	v_mfma_f32_16x16x32_bf16 v[44:47], v[144:147], v[210:213], 0
	v_mfma_f32_16x16x32_bf16 v[40:43], v[144:147], v[218:221], 0
	v_mfma_f32_16x16x32_bf16 v[36:39], v[144:147], v[226:229], 0
	v_mfma_f32_16x16x32_bf16 v[32:35], v[144:147], v[234:237], 0
	v_mfma_f32_16x16x32_bf16 v[28:31], v[148:151], v[210:213], 0
	v_mfma_f32_16x16x32_bf16 v[24:27], v[148:151], v[218:221], 0
	v_mfma_f32_16x16x32_bf16 v[20:23], v[148:151], v[226:229], 0
	v_mfma_f32_16x16x32_bf16 v[244:247], v[148:151], v[234:237], 0
	v_mfma_f32_16x16x32_bf16 v[12:15], v[152:155], v[210:213], 0
	v_mfma_f32_16x16x32_bf16 v[8:11], v[152:155], v[218:221], 0
	v_mfma_f32_16x16x32_bf16 v[4:7], v[152:155], v[226:229], 0
	v_mfma_f32_16x16x32_bf16 v[248:251], v[152:155], v[234:237], 0
	ds_read_b128 v[140:143], v17 offset:128
	ds_read_b128 v[144:147], v17 offset:8576
	ds_read_b128 v[148:151], v17 offset:17024
	ds_read_b128 v[152:155], v17 offset:25472
	s_waitcnt lgkmcnt(4)
	v_mfma_f32_16x16x32_bf16 v[60:63], v[156:159], v[214:217], v[60:63]
	v_mfma_f32_16x16x32_bf16 v[56:59], v[156:159], v[222:225], v[56:59]
	v_mfma_f32_16x16x32_bf16 v[52:55], v[156:159], v[230:233], v[52:55]
	v_mfma_f32_16x16x32_bf16 v[48:51], v[156:159], v[238:241], v[48:51]
	v_mfma_f32_16x16x32_bf16 v[44:47], v[160:163], v[214:217], v[44:47]
	v_mfma_f32_16x16x32_bf16 v[40:43], v[160:163], v[222:225], v[40:43]
	v_mfma_f32_16x16x32_bf16 v[36:39], v[160:163], v[230:233], v[36:39]
	v_mfma_f32_16x16x32_bf16 v[32:35], v[160:163], v[238:241], v[32:35]
	v_mfma_f32_16x16x32_bf16 v[28:31], v[164:167], v[214:217], v[28:31]
	v_mfma_f32_16x16x32_bf16 v[24:27], v[164:167], v[222:225], v[24:27]
	v_mfma_f32_16x16x32_bf16 v[20:23], v[164:167], v[230:233], v[20:23]
	v_mfma_f32_16x16x32_bf16 v[244:247], v[164:167], v[238:241], v[244:247]
	v_mfma_f32_16x16x32_bf16 v[12:15], v[168:171], v[214:217], v[12:15]
	v_mfma_f32_16x16x32_bf16 v[8:11], v[168:171], v[222:225], v[8:11]
	v_mfma_f32_16x16x32_bf16 v[4:7], v[168:171], v[230:233], v[4:7]
	v_mfma_f32_16x16x32_bf16 v[248:251], v[168:171], v[238:241], v[248:251]
	ds_read_b128 v[156:159], v17 offset:192
	ds_read_b128 v[160:163], v17 offset:8640
	ds_read_b128 v[164:167], v17 offset:17088
	ds_read_b128 v[168:171], v17 offset:25536
	global_load_dwordx4 v[210:213], v252, s[96:97] offset:256
	global_load_dwordx4 v[214:217], v252, s[96:97] offset:320
	global_load_dwordx4 v[218:221], v252, s[98:99] offset:256
	global_load_dwordx4 v[222:225], v252, s[98:99] offset:320
	global_load_dwordx4 v[226:229], v253, s[96:97] offset:256
	global_load_dwordx4 v[230:233], v253, s[96:97] offset:320
	global_load_dwordx4 v[234:237], v253, s[98:99] offset:256
	global_load_dwordx4 v[238:241], v253, s[98:99] offset:320
	s_waitcnt vmcnt(8)
	s_waitcnt lgkmcnt(4)
	v_mfma_f32_16x16x32_bf16 v[60:63], v[140:143], v[74:77], v[60:63]
	v_mfma_f32_16x16x32_bf16 v[56:59], v[140:143], v[82:85], v[56:59]
	v_mfma_f32_16x16x32_bf16 v[52:55], v[140:143], v[90:93], v[52:55]
	v_mfma_f32_16x16x32_bf16 v[48:51], v[140:143], v[172:175], v[48:51]
	v_mfma_f32_16x16x32_bf16 v[44:47], v[144:147], v[74:77], v[44:47]
	v_mfma_f32_16x16x32_bf16 v[40:43], v[144:147], v[82:85], v[40:43]
	v_mfma_f32_16x16x32_bf16 v[36:39], v[144:147], v[90:93], v[36:39]
	v_mfma_f32_16x16x32_bf16 v[32:35], v[144:147], v[172:175], v[32:35]
	v_mfma_f32_16x16x32_bf16 v[28:31], v[148:151], v[74:77], v[28:31]
	v_mfma_f32_16x16x32_bf16 v[24:27], v[148:151], v[82:85], v[24:27]
	v_mfma_f32_16x16x32_bf16 v[20:23], v[148:151], v[90:93], v[20:23]
	v_mfma_f32_16x16x32_bf16 v[244:247], v[148:151], v[172:175], v[244:247]
	v_mfma_f32_16x16x32_bf16 v[12:15], v[152:155], v[74:77], v[12:15]
	v_mfma_f32_16x16x32_bf16 v[8:11], v[152:155], v[82:85], v[8:11]
	v_mfma_f32_16x16x32_bf16 v[4:7], v[152:155], v[90:93], v[4:7]
	v_mfma_f32_16x16x32_bf16 v[248:251], v[152:155], v[172:175], v[248:251]
	ds_read_b128 v[140:143], v17 offset:256
	ds_read_b128 v[144:147], v17 offset:8704
	ds_read_b128 v[148:151], v17 offset:17152
	ds_read_b128 v[152:155], v17 offset:25600
	s_waitcnt lgkmcnt(4)
; #define MFMA(a, b, c) __builtin_amdgcn_mfma_f32_16x16x32_bf16((a), (b), (c), 0, 0, 0)
; __device__ __forceinline__ void xattn_item(const Params& p, char* smem, const int tile, const int hm) {
;     ...
;     for (int kt = 0; kt < 4; ++kt) {
; #pragma unroll
;       for (int i = 0; i < 8; ++i) {
;         const int c = tid + 256 * i, row = c >> 3, cc = c & 7;
;         st[i] = *(const u32x4*)(kmem + (size_t)(b * 256 + row) * 1024 + hm * 256 + kt * 64 + cc * 8);
;       }
;       __syncthreads();
; #pragma unroll
;       for (int i = 0; i < 8; ++i) {
;         const int c = tid + 256 * i, row = c >> 3, cc = c & 7;
;         *(u32x4*)(sT + row * 72 + cc * 8) = st[i];
;       }
;       __syncthreads();
; #pragma unroll
;       for (int ks = 0; ks < 2; ++ks) {
;         bf16x8 af[4], bfr[4];
; #pragma unroll
;         for (int m = 0; m < 4; ++m) af[m] = *(const bf16x8*)(sQ + (m * 16 + l15) * 264 + kt * 64 + ks * 32 + lq * 8);
; #pragma unroll
;         for (int n = 0; n < 4; ++n) bfr[n] = *(const bf16x8*)(sT + (w * 64 + n * 16 + l15) * 72 + ks * 32 + lq * 8);
; #pragma unroll
;         for (int m = 0; m < 4; ++m)
; #pragma unroll
;           for (int n = 0; n < 4; ++n) acc[m][n] = MFMA(af[m], bfr[n], acc[m][n]);
;       }
	v_mfma_f32_16x16x32_bf16 v[60:63], v[156:159], v[78:81], v[60:63]
	v_mfma_f32_16x16x32_bf16 v[56:59], v[156:159], v[86:89], v[56:59]
	v_mfma_f32_16x16x32_bf16 v[52:55], v[156:159], v[114:117], v[52:55]
	v_mfma_f32_16x16x32_bf16 v[48:51], v[156:159], v[176:179], v[48:51]
	v_mfma_f32_16x16x32_bf16 v[44:47], v[160:163], v[78:81], v[44:47]
	v_mfma_f32_16x16x32_bf16 v[40:43], v[160:163], v[86:89], v[40:43]
	v_mfma_f32_16x16x32_bf16 v[36:39], v[160:163], v[114:117], v[36:39]
	v_mfma_f32_16x16x32_bf16 v[32:35], v[160:163], v[176:179], v[32:35]
	v_mfma_f32_16x16x32_bf16 v[28:31], v[164:167], v[78:81], v[28:31]
	v_mfma_f32_16x16x32_bf16 v[24:27], v[164:167], v[86:89], v[24:27]
	v_mfma_f32_16x16x32_bf16 v[20:23], v[164:167], v[114:117], v[20:23]
	v_mfma_f32_16x16x32_bf16 v[244:247], v[164:167], v[176:179], v[244:247]
	v_mfma_f32_16x16x32_bf16 v[12:15], v[168:171], v[78:81], v[12:15]
	v_mfma_f32_16x16x32_bf16 v[8:11], v[168:171], v[86:89], v[8:11]
	v_mfma_f32_16x16x32_bf16 v[4:7], v[168:171], v[114:117], v[4:7]
	v_mfma_f32_16x16x32_bf16 v[248:251], v[168:171], v[176:179], v[248:251]
	ds_read_b128 v[156:159], v17 offset:320
	ds_read_b128 v[160:163], v17 offset:8768
	ds_read_b128 v[164:167], v17 offset:17216
	ds_read_b128 v[168:171], v17 offset:25664
	global_load_dwordx4 v[74:77], v252, s[96:97] offset:384
	global_load_dwordx4 v[78:81], v252, s[96:97] offset:448
	global_load_dwordx4 v[82:85], v252, s[98:99] offset:384
	global_load_dwordx4 v[86:89], v252, s[98:99] offset:448
	global_load_dwordx4 v[90:93], v253, s[96:97] offset:384
	global_load_dwordx4 v[114:117], v253, s[96:97] offset:448
	global_load_dwordx4 v[172:175], v253, s[98:99] offset:384
	global_load_dwordx4 v[176:179], v253, s[98:99] offset:448
	s_waitcnt vmcnt(8)
	s_waitcnt lgkmcnt(4)
	v_mfma_f32_16x16x32_bf16 v[60:63], v[140:143], v[210:213], v[60:63]
	v_mfma_f32_16x16x32_bf16 v[56:59], v[140:143], v[218:221], v[56:59]
	v_mfma_f32_16x16x32_bf16 v[52:55], v[140:143], v[226:229], v[52:55]
	v_mfma_f32_16x16x32_bf16 v[48:51], v[140:143], v[234:237], v[48:51]
	v_mfma_f32_16x16x32_bf16 v[44:47], v[144:147], v[210:213], v[44:47]
	v_mfma_f32_16x16x32_bf16 v[40:43], v[144:147], v[218:221], v[40:43]
	v_mfma_f32_16x16x32_bf16 v[36:39], v[144:147], v[226:229], v[36:39]
	v_mfma_f32_16x16x32_bf16 v[32:35], v[144:147], v[234:237], v[32:35]
	v_mfma_f32_16x16x32_bf16 v[28:31], v[148:151], v[210:213], v[28:31]
	v_mfma_f32_16x16x32_bf16 v[24:27], v[148:151], v[218:221], v[24:27]
	v_mfma_f32_16x16x32_bf16 v[20:23], v[148:151], v[226:229], v[20:23]
	v_mfma_f32_16x16x32_bf16 v[244:247], v[148:151], v[234:237], v[244:247]
	v_mfma_f32_16x16x32_bf16 v[12:15], v[152:155], v[210:213], v[12:15]
	v_mfma_f32_16x16x32_bf16 v[8:11], v[152:155], v[218:221], v[8:11]
	v_mfma_f32_16x16x32_bf16 v[4:7], v[152:155], v[226:229], v[4:7]
	v_mfma_f32_16x16x32_bf16 v[248:251], v[152:155], v[234:237], v[248:251]
	ds_read_b128 v[140:143], v17 offset:384
	ds_read_b128 v[144:147], v17 offset:8832
	ds_read_b128 v[148:151], v17 offset:17280
	ds_read_b128 v[152:155], v17 offset:25728
	s_waitcnt lgkmcnt(4)
	v_mfma_f32_16x16x32_bf16 v[60:63], v[156:159], v[214:217], v[60:63]
	v_mfma_f32_16x16x32_bf16 v[56:59], v[156:159], v[222:225], v[56:59]
	v_mfma_f32_16x16x32_bf16 v[52:55], v[156:159], v[230:233], v[52:55]
	v_mfma_f32_16x16x32_bf16 v[48:51], v[156:159], v[238:241], v[48:51]
	v_mfma_f32_16x16x32_bf16 v[44:47], v[160:163], v[214:217], v[44:47]
	v_mfma_f32_16x16x32_bf16 v[40:43], v[160:163], v[222:225], v[40:43]
	v_mfma_f32_16x16x32_bf16 v[36:39], v[160:163], v[230:233], v[36:39]
	v_mfma_f32_16x16x32_bf16 v[32:35], v[160:163], v[238:241], v[32:35]
	v_mfma_f32_16x16x32_bf16 v[28:31], v[164:167], v[214:217], v[28:31]
	v_mfma_f32_16x16x32_bf16 v[24:27], v[164:167], v[222:225], v[24:27]
	v_mfma_f32_16x16x32_bf16 v[20:23], v[164:167], v[230:233], v[20:23]
	v_mfma_f32_16x16x32_bf16 v[244:247], v[164:167], v[238:241], v[244:247]
	v_mfma_f32_16x16x32_bf16 v[12:15], v[168:171], v[214:217], v[12:15]
	v_mfma_f32_16x16x32_bf16 v[8:11], v[168:171], v[222:225], v[8:11]
	v_mfma_f32_16x16x32_bf16 v[4:7], v[168:171], v[230:233], v[4:7]
	v_mfma_f32_16x16x32_bf16 v[248:251], v[168:171], v[238:241], v[248:251]
	ds_read_b128 v[156:159], v17 offset:448
	ds_read_b128 v[160:163], v17 offset:8896
	ds_read_b128 v[164:167], v17 offset:17344
	ds_read_b128 v[168:171], v17 offset:25792
	s_waitcnt vmcnt(0)
	s_waitcnt lgkmcnt(4)
	v_mfma_f32_16x16x32_bf16 v[60:63], v[140:143], v[74:77], v[60:63]
	v_mfma_f32_16x16x32_bf16 v[56:59], v[140:143], v[82:85], v[56:59]
	v_mfma_f32_16x16x32_bf16 v[52:55], v[140:143], v[90:93], v[52:55]
	v_mfma_f32_16x16x32_bf16 v[48:51], v[140:143], v[172:175], v[48:51]
	v_mfma_f32_16x16x32_bf16 v[44:47], v[144:147], v[74:77], v[44:47]
	v_mfma_f32_16x16x32_bf16 v[40:43], v[144:147], v[82:85], v[40:43]
	v_mfma_f32_16x16x32_bf16 v[36:39], v[144:147], v[90:93], v[36:39]
	v_mfma_f32_16x16x32_bf16 v[32:35], v[144:147], v[172:175], v[32:35]
	v_mfma_f32_16x16x32_bf16 v[28:31], v[148:151], v[74:77], v[28:31]
	v_mfma_f32_16x16x32_bf16 v[24:27], v[148:151], v[82:85], v[24:27]
	v_mfma_f32_16x16x32_bf16 v[20:23], v[148:151], v[90:93], v[20:23]
	v_mfma_f32_16x16x32_bf16 v[244:247], v[148:151], v[172:175], v[244:247]
	v_mfma_f32_16x16x32_bf16 v[12:15], v[152:155], v[74:77], v[12:15]
	v_mfma_f32_16x16x32_bf16 v[8:11], v[152:155], v[82:85], v[8:11]
	v_mfma_f32_16x16x32_bf16 v[4:7], v[152:155], v[90:93], v[4:7]
	v_mfma_f32_16x16x32_bf16 v[248:251], v[152:155], v[172:175], v[248:251]
	s_waitcnt lgkmcnt(0)
; #define MFMA(a, b, c) __builtin_amdgcn_mfma_f32_16x16x32_bf16((a), (b), (c), 0, 0, 0)
; __device__ __forceinline__ void xattn_item(const Params& p, char* smem, const int tile, const int hm) {
;     ...
;           for (int n = 0; n < 4; ++n) acc[m][n] = MFMA(af[m], bfr[n], acc[m][n]);
;       }
;     }
; #pragma unroll
;     for (int m = 0; m < 4; ++m)
; #pragma unroll
;       for (int j = 0; j < 4; ++j) {
;         float mx = fmaxf(fmaxf(acc[m][0][j], acc[m][1][j]), fmaxf(acc[m][2][j], acc[m][3][j]));
;         mx = row16_max(mx);
;         if (l15 == 0) sMax[w * 64 + m * 16 + lq * 4 + j] = mx;
;       }
	v_mfma_f32_16x16x32_bf16 v[60:63], v[156:159], v[78:81], v[60:63]
	v_mfma_f32_16x16x32_bf16 v[56:59], v[156:159], v[86:89], v[56:59]
	v_mfma_f32_16x16x32_bf16 v[52:55], v[156:159], v[114:117], v[52:55]
	v_mfma_f32_16x16x32_bf16 v[48:51], v[156:159], v[176:179], v[48:51]
	v_mfma_f32_16x16x32_bf16 v[44:47], v[160:163], v[78:81], v[44:47]
	v_mfma_f32_16x16x32_bf16 v[40:43], v[160:163], v[86:89], v[40:43]
	v_mfma_f32_16x16x32_bf16 v[36:39], v[160:163], v[114:117], v[36:39]
	v_mfma_f32_16x16x32_bf16 v[32:35], v[160:163], v[176:179], v[32:35]
	v_mfma_f32_16x16x32_bf16 v[28:31], v[164:167], v[78:81], v[28:31]
	v_mfma_f32_16x16x32_bf16 v[24:27], v[164:167], v[86:89], v[24:27]
	v_mfma_f32_16x16x32_bf16 v[20:23], v[164:167], v[114:117], v[20:23]
	v_mfma_f32_16x16x32_bf16 v[244:247], v[164:167], v[176:179], v[244:247]
	v_mfma_f32_16x16x32_bf16 v[12:15], v[168:171], v[78:81], v[12:15]
	v_mfma_f32_16x16x32_bf16 v[8:11], v[168:171], v[86:89], v[8:11]
	v_mfma_f32_16x16x32_bf16 v[4:7], v[168:171], v[114:117], v[4:7]
	v_mfma_f32_16x16x32_bf16 v[248:251], v[168:171], v[176:179], v[248:251]
	s_nop 7
	v_max_f32_e32 v2, v52, v52
	v_max_f32_e32 v1, v48, v48
	v_max_f32_e32 v1, v2, v1
	v_max3_f32 v1, v60, v56, v1
	v_and_b32_e32 v96, 0xffffffc0, v16
	v_lshl_add_u32 v0, v96, 2, v125
	s_nop 1
	v_mov_b32_dpp v2, v1 quad_perm:[1,0,3,2] row_mask:0xf bank_mask:0xf bound_ctrl:1
	v_max_f32_e32 v2, v2, v2
	v_max_f32_e32 v1, v1, v2
	s_nop 1
	v_mov_b32_dpp v2, v1 quad_perm:[2,3,0,1] row_mask:0xf bank_mask:0xf bound_ctrl:1
	v_max_f32_e32 v2, v2, v2
	v_max_f32_e32 v1, v1, v2
	s_nop 1
	v_mov_b32_dpp v2, v1 row_half_mirror row_mask:0xf bank_mask:0xf bound_ctrl:1
	v_max_f32_e32 v2, v2, v2
	v_max_f32_e32 v75, v1, v2
	v_add_u32_e32 v74, v0, v64
	s_nop 1
	v_mov_b32_dpp v76, v75 row_ror:8 row_mask:0xf bank_mask:0xf bound_ctrl:1
	s_nop 1
	v_mov_b32_e32 v16, v244
	v_mov_b32_e32 v17, v245
	v_mov_b32_e32 v18, v246
	v_mov_b32_e32 v19, v247
	v_mov_b32_e32 v0, v248
	v_mov_b32_e32 v1, v249
	v_mov_b32_e32 v2, v250
	v_mov_b32_e32 v3, v251
	s_and_saveexec_b64 s[4:5], vcc
	v_max_f32_e32 v76, v76, v76
	v_max_f32_e32 v75, v75, v75
	v_max_f32_e32 v75, v75, v76
	ds_write_b32 v74, v75
	s_or_b64 exec, exec, s[4:5]
	v_max_f32_e32 v75, v49, v49
	v_max_f32_e32 v76, v53, v53
	v_max_f32_e32 v75, v76, v75
	v_max3_f32 v75, v61, v57, v75
	s_nop 1
	v_mov_b32_dpp v76, v75 quad_perm:[1,0,3,2] row_mask:0xf bank_mask:0xf bound_ctrl:1
	v_max_f32_e32 v76, v76, v76
	v_max_f32_e32 v75, v75, v76
	s_nop 1
	v_mov_b32_dpp v76, v75 quad_perm:[2,3,0,1] row_mask:0xf bank_mask:0xf bound_ctrl:1
	v_max_f32_e32 v76, v76, v76
	v_max_f32_e32 v75, v75, v76
	s_nop 1
	v_mov_b32_dpp v76, v75 row_half_mirror row_mask:0xf bank_mask:0xf bound_ctrl:1
	v_max_f32_e32 v76, v76, v76
	v_max_f32_e32 v75, v75, v76
	s_nop 1
	v_mov_b32_dpp v76, v75 row_ror:8 row_mask:0xf bank_mask:0xf bound_ctrl:1
	s_and_saveexec_b64 s[4:5], vcc
	v_max_f32_e32 v76, v76, v76
	v_max_f32_e32 v75, v75, v75
	v_max_f32_e32 v75, v75, v76
	ds_write_b32 v74, v75 offset:4
	s_or_b64 exec, exec, s[4:5]
	v_max_f32_e32 v75, v50, v50
	v_max_f32_e32 v76, v54, v54
	v_max_f32_e32 v75, v76, v75
	v_max3_f32 v75, v62, v58, v75
	s_nop 1
	v_mov_b32_dpp v76, v75 quad_perm:[1,0,3,2] row_mask:0xf bank_mask:0xf bound_ctrl:1
	v_max_f32_e32 v76, v76, v76
	v_max_f32_e32 v75, v75, v76
	s_nop 1
	v_mov_b32_dpp v76, v75 quad_perm:[2,3,0,1] row_mask:0xf bank_mask:0xf bound_ctrl:1
	v_max_f32_e32 v76, v76, v76
	v_max_f32_e32 v75, v75, v76
	s_nop 1
	v_mov_b32_dpp v76, v75 row_half_mirror row_mask:0xf bank_mask:0xf bound_ctrl:1
	v_max_f32_e32 v76, v76, v76
	v_max_f32_e32 v75, v75, v76
	s_nop 1
	v_mov_b32_dpp v76, v75 row_ror:8 row_mask:0xf bank_mask:0xf bound_ctrl:1
	s_and_saveexec_b64 s[4:5], vcc
	v_max_f32_e32 v76, v76, v76
	v_max_f32_e32 v75, v75, v75
	v_max_f32_e32 v75, v75, v76
	ds_write_b32 v74, v75 offset:8
	s_or_b64 exec, exec, s[4:5]
	v_max_f32_e32 v75, v51, v51
	v_max_f32_e32 v76, v55, v55
	v_max_f32_e32 v75, v76, v75
	v_max3_f32 v75, v63, v59, v75
	s_nop 1
	v_mov_b32_dpp v76, v75 quad_perm:[1,0,3,2] row_mask:0xf bank_mask:0xf bound_ctrl:1
	v_max_f32_e32 v76, v76, v76
	v_max_f32_e32 v75, v75, v76
	s_nop 1
	v_mov_b32_dpp v76, v75 quad_perm:[2,3,0,1] row_mask:0xf bank_mask:0xf bound_ctrl:1
	v_max_f32_e32 v76, v76, v76
	v_max_f32_e32 v75, v75, v76
	s_nop 1
	v_mov_b32_dpp v76, v75 row_half_mirror row_mask:0xf bank_mask:0xf bound_ctrl:1
	v_max_f32_e32 v76, v76, v76
	v_max_f32_e32 v75, v75, v76
	s_nop 1
	v_mov_b32_dpp v76, v75 row_ror:8 row_mask:0xf bank_mask:0xf bound_ctrl:1
	s_and_saveexec_b64 s[4:5], vcc
	v_max_f32_e32 v76, v76, v76
	v_max_f32_e32 v75, v75, v75
	v_max_f32_e32 v75, v75, v76
	ds_write_b32 v74, v75 offset:12
	s_or_b64 exec, exec, s[4:5]
	v_max_f32_e32 v75, v32, v32
	v_max_f32_e32 v76, v36, v36
	v_max_f32_e32 v75, v76, v75
	v_max3_f32 v75, v44, v40, v75
	s_nop 1
	v_mov_b32_dpp v76, v75 quad_perm:[1,0,3,2] row_mask:0xf bank_mask:0xf bound_ctrl:1
	v_max_f32_e32 v76, v76, v76
	v_max_f32_e32 v75, v75, v76
	s_nop 1
	v_mov_b32_dpp v76, v75 quad_perm:[2,3,0,1] row_mask:0xf bank_mask:0xf bound_ctrl:1
	v_max_f32_e32 v76, v76, v76
	v_max_f32_e32 v75, v75, v76
	s_nop 1
	v_mov_b32_dpp v76, v75 row_half_mirror row_mask:0xf bank_mask:0xf bound_ctrl:1
	v_max_f32_e32 v76, v76, v76
	v_max_f32_e32 v75, v75, v76
	s_nop 1
	v_mov_b32_dpp v76, v75 row_ror:8 row_mask:0xf bank_mask:0xf bound_ctrl:1
	s_and_saveexec_b64 s[4:5], vcc
	v_max_f32_e32 v76, v76, v76
	v_max_f32_e32 v75, v75, v75
	v_max_f32_e32 v75, v75, v76
	ds_write_b32 v74, v75 offset:64
	s_or_b64 exec, exec, s[4:5]
	v_max_f32_e32 v75, v33, v33
	v_max_f32_e32 v76, v37, v37
	v_max_f32_e32 v75, v76, v75
	v_max3_f32 v75, v45, v41, v75
	s_nop 1
; __device__ __forceinline__ void xattn_item(const Params& p, char* smem, const int tile, const int hm) {
;     ...
; #pragma unroll
;     for (int m = 0; m < 4; ++m)
; #pragma unroll
;       for (int j = 0; j < 4; ++j) {
;         float mx = fmaxf(fmaxf(acc[m][0][j], acc[m][1][j]), fmaxf(acc[m][2][j], acc[m][3][j]));
;         mx = row16_max(mx);
;         if (l15 == 0) sMax[w * 64 + m * 16 + lq * 4 + j] = mx;
;       }
	v_mov_b32_dpp v76, v75 quad_perm:[1,0,3,2] row_mask:0xf bank_mask:0xf bound_ctrl:1
	v_max_f32_e32 v76, v76, v76
	v_max_f32_e32 v75, v75, v76
	s_nop 1
	v_mov_b32_dpp v76, v75 quad_perm:[2,3,0,1] row_mask:0xf bank_mask:0xf bound_ctrl:1
	v_max_f32_e32 v76, v76, v76
	v_max_f32_e32 v75, v75, v76
	s_nop 1
	v_mov_b32_dpp v76, v75 row_half_mirror row_mask:0xf bank_mask:0xf bound_ctrl:1
	v_max_f32_e32 v76, v76, v76
	v_max_f32_e32 v75, v75, v76
	s_nop 1
	v_mov_b32_dpp v76, v75 row_ror:8 row_mask:0xf bank_mask:0xf bound_ctrl:1
	s_and_saveexec_b64 s[4:5], vcc
	v_max_f32_e32 v76, v76, v76
	v_max_f32_e32 v75, v75, v75
	v_max_f32_e32 v75, v75, v76
	ds_write_b32 v74, v75 offset:68
	s_or_b64 exec, exec, s[4:5]
	v_max_f32_e32 v75, v34, v34
	v_max_f32_e32 v76, v38, v38
	v_max_f32_e32 v75, v76, v75
	v_max3_f32 v75, v46, v42, v75
	s_nop 1
	v_mov_b32_dpp v76, v75 quad_perm:[1,0,3,2] row_mask:0xf bank_mask:0xf bound_ctrl:1
	v_max_f32_e32 v76, v76, v76
	v_max_f32_e32 v75, v75, v76
	s_nop 1
	v_mov_b32_dpp v76, v75 quad_perm:[2,3,0,1] row_mask:0xf bank_mask:0xf bound_ctrl:1
	v_max_f32_e32 v76, v76, v76
	v_max_f32_e32 v75, v75, v76
	s_nop 1
	v_mov_b32_dpp v76, v75 row_half_mirror row_mask:0xf bank_mask:0xf bound_ctrl:1
	v_max_f32_e32 v76, v76, v76
	v_max_f32_e32 v75, v75, v76
	s_nop 1
	v_mov_b32_dpp v76, v75 row_ror:8 row_mask:0xf bank_mask:0xf bound_ctrl:1
	s_and_saveexec_b64 s[4:5], vcc
	v_max_f32_e32 v76, v76, v76
	v_max_f32_e32 v75, v75, v75
	v_max_f32_e32 v75, v75, v76
	ds_write_b32 v74, v75 offset:72
	s_or_b64 exec, exec, s[4:5]
	v_max_f32_e32 v75, v35, v35
	v_max_f32_e32 v76, v39, v39
	v_max_f32_e32 v75, v76, v75
	v_max3_f32 v75, v47, v43, v75
	s_nop 1
	v_mov_b32_dpp v76, v75 quad_perm:[1,0,3,2] row_mask:0xf bank_mask:0xf bound_ctrl:1
	v_max_f32_e32 v76, v76, v76
	v_max_f32_e32 v75, v75, v76
	s_nop 1
	v_mov_b32_dpp v76, v75 quad_perm:[2,3,0,1] row_mask:0xf bank_mask:0xf bound_ctrl:1
	v_max_f32_e32 v76, v76, v76
	v_max_f32_e32 v75, v75, v76
	s_nop 1
	v_mov_b32_dpp v76, v75 row_half_mirror row_mask:0xf bank_mask:0xf bound_ctrl:1
	v_max_f32_e32 v76, v76, v76
	v_max_f32_e32 v75, v75, v76
	s_nop 1
	v_mov_b32_dpp v76, v75 row_ror:8 row_mask:0xf bank_mask:0xf bound_ctrl:1
	s_and_saveexec_b64 s[4:5], vcc
	v_max_f32_e32 v76, v76, v76
	v_max_f32_e32 v75, v75, v75
	v_max_f32_e32 v75, v75, v76
	ds_write_b32 v74, v75 offset:76
	s_or_b64 exec, exec, s[4:5]
	v_max_f32_e32 v75, v16, v16
	v_max_f32_e32 v76, v20, v20
	v_max_f32_e32 v75, v76, v75
	v_max3_f32 v75, v28, v24, v75
	s_nop 1
	v_mov_b32_dpp v76, v75 quad_perm:[1,0,3,2] row_mask:0xf bank_mask:0xf bound_ctrl:1
	v_max_f32_e32 v76, v76, v76
	v_max_f32_e32 v75, v75, v76
	s_nop 1
	v_mov_b32_dpp v76, v75 quad_perm:[2,3,0,1] row_mask:0xf bank_mask:0xf bound_ctrl:1
	v_max_f32_e32 v76, v76, v76
	v_max_f32_e32 v75, v75, v76
	s_nop 1
	v_mov_b32_dpp v76, v75 row_half_mirror row_mask:0xf bank_mask:0xf bound_ctrl:1
	v_max_f32_e32 v76, v76, v76
	v_max_f32_e32 v75, v75, v76
	s_nop 1
	v_mov_b32_dpp v76, v75 row_ror:8 row_mask:0xf bank_mask:0xf bound_ctrl:1
	s_and_saveexec_b64 s[4:5], vcc
	v_max_f32_e32 v76, v76, v76
	v_max_f32_e32 v75, v75, v75
	v_max_f32_e32 v75, v75, v76
	ds_write_b32 v74, v75 offset:128
	s_or_b64 exec, exec, s[4:5]
	v_max_f32_e32 v75, v17, v17
	v_max_f32_e32 v76, v21, v21
	v_max_f32_e32 v75, v76, v75
	v_max3_f32 v75, v29, v25, v75
	s_nop 1
	v_mov_b32_dpp v76, v75 quad_perm:[1,0,3,2] row_mask:0xf bank_mask:0xf bound_ctrl:1
	v_max_f32_e32 v76, v76, v76
	v_max_f32_e32 v75, v75, v76
	s_nop 1
	v_mov_b32_dpp v76, v75 quad_perm:[2,3,0,1] row_mask:0xf bank_mask:0xf bound_ctrl:1
	v_max_f32_e32 v76, v76, v76
	v_max_f32_e32 v75, v75, v76
	s_nop 1
	v_mov_b32_dpp v76, v75 row_half_mirror row_mask:0xf bank_mask:0xf bound_ctrl:1
	v_max_f32_e32 v76, v76, v76
	v_max_f32_e32 v75, v75, v76
	s_nop 1
	v_mov_b32_dpp v76, v75 row_ror:8 row_mask:0xf bank_mask:0xf bound_ctrl:1
	s_and_saveexec_b64 s[4:5], vcc
	v_max_f32_e32 v76, v76, v76
	v_max_f32_e32 v75, v75, v75
	v_max_f32_e32 v75, v75, v76
	ds_write_b32 v74, v75 offset:132
	s_or_b64 exec, exec, s[4:5]
	v_max_f32_e32 v75, v18, v18
	v_max_f32_e32 v76, v22, v22
	v_max_f32_e32 v75, v76, v75
	v_max3_f32 v75, v30, v26, v75
	s_nop 1
	v_mov_b32_dpp v76, v75 quad_perm:[1,0,3,2] row_mask:0xf bank_mask:0xf bound_ctrl:1
	v_max_f32_e32 v76, v76, v76
	v_max_f32_e32 v75, v75, v76
	s_nop 1
	v_mov_b32_dpp v76, v75 quad_perm:[2,3,0,1] row_mask:0xf bank_mask:0xf bound_ctrl:1
	v_max_f32_e32 v76, v76, v76
	v_max_f32_e32 v75, v75, v76
	s_nop 1
	v_mov_b32_dpp v76, v75 row_half_mirror row_mask:0xf bank_mask:0xf bound_ctrl:1
	v_max_f32_e32 v76, v76, v76
	v_max_f32_e32 v75, v75, v76
	s_nop 1
	v_mov_b32_dpp v76, v75 row_ror:8 row_mask:0xf bank_mask:0xf bound_ctrl:1
	s_and_saveexec_b64 s[4:5], vcc
	v_max_f32_e32 v76, v76, v76
	v_max_f32_e32 v75, v75, v75
	v_max_f32_e32 v75, v75, v76
	ds_write_b32 v74, v75 offset:136
	s_or_b64 exec, exec, s[4:5]
	v_max_f32_e32 v75, v19, v19
	v_max_f32_e32 v76, v23, v23
	v_max_f32_e32 v75, v76, v75
	v_max3_f32 v75, v31, v27, v75
	s_nop 1
	v_mov_b32_dpp v76, v75 quad_perm:[1,0,3,2] row_mask:0xf bank_mask:0xf bound_ctrl:1
	v_max_f32_e32 v76, v76, v76
	v_max_f32_e32 v75, v75, v76
	s_nop 1
	v_mov_b32_dpp v76, v75 quad_perm:[2,3,0,1] row_mask:0xf bank_mask:0xf bound_ctrl:1
	v_max_f32_e32 v76, v76, v76
	v_max_f32_e32 v75, v75, v76
	s_nop 1
	v_mov_b32_dpp v76, v75 row_half_mirror row_mask:0xf bank_mask:0xf bound_ctrl:1
	v_max_f32_e32 v76, v76, v76
	v_max_f32_e32 v75, v75, v76
	s_nop 1
	v_mov_b32_dpp v76, v75 row_ror:8 row_mask:0xf bank_mask:0xf bound_ctrl:1
	s_and_saveexec_b64 s[4:5], vcc
	v_max_f32_e32 v76, v76, v76
	v_max_f32_e32 v75, v75, v75
	v_max_f32_e32 v75, v75, v76
; __device__ __forceinline__ void xattn_item(const Params& p, char* smem, const int tile, const int hm) {
;     ...
; #pragma unroll
;     for (int m = 0; m < 4; ++m)
; #pragma unroll
;       for (int j = 0; j < 4; ++j) {
;         float mx = fmaxf(fmaxf(acc[m][0][j], acc[m][1][j]), fmaxf(acc[m][2][j], acc[m][3][j]));
;         mx = row16_max(mx);
;         if (l15 == 0) sMax[w * 64 + m * 16 + lq * 4 + j] = mx;
;       }
;     __syncthreads();
; #pragma unroll
;     for (int m = 0; m < 4; ++m)
; #pragma unroll
;       for (int j = 0; j < 4; ++j) {
;         const int row = m * 16 + lq * 4 + j;
;         const float gmx = fmaxf(fmaxf(sMax[row], sMax[64 + row]), fmaxf(sMax[128 + row], sMax[192 + row]));
;         float sum = 0.f;
; #pragma unroll
;         for (int n = 0; n < 4; ++n) {
;           const float e = __expf((acc[m][n][j] - gmx) * 0.0625f);
;           sum += e;
;           sQ[row * 264 + w * 64 + n * 16 + l15] = f2bf(e);
;         }
;         sum = row16_sum(sum);
;         if (l15 == 0) sSum[w * 64 + row] = sum;
;       }
	ds_write_b32 v74, v75 offset:140
	s_or_b64 exec, exec, s[4:5]
	v_max_f32_e32 v75, v0, v0
	v_max_f32_e32 v76, v4, v4
	v_max_f32_e32 v75, v76, v75
	v_max3_f32 v75, v12, v8, v75
	s_nop 1
	v_mov_b32_dpp v76, v75 quad_perm:[1,0,3,2] row_mask:0xf bank_mask:0xf bound_ctrl:1
	v_max_f32_e32 v76, v76, v76
	v_max_f32_e32 v75, v75, v76
	s_nop 1
	v_mov_b32_dpp v76, v75 quad_perm:[2,3,0,1] row_mask:0xf bank_mask:0xf bound_ctrl:1
	v_max_f32_e32 v76, v76, v76
	v_max_f32_e32 v75, v75, v76
	s_nop 1
	v_mov_b32_dpp v76, v75 row_half_mirror row_mask:0xf bank_mask:0xf bound_ctrl:1
	v_max_f32_e32 v76, v76, v76
	v_max_f32_e32 v75, v75, v76
	s_nop 1
	v_mov_b32_dpp v76, v75 row_ror:8 row_mask:0xf bank_mask:0xf bound_ctrl:1
	s_and_saveexec_b64 s[4:5], vcc
	v_max_f32_e32 v76, v76, v76
	v_max_f32_e32 v75, v75, v75
	v_max_f32_e32 v75, v75, v76
	ds_write_b32 v74, v75 offset:192
	s_or_b64 exec, exec, s[4:5]
	v_max_f32_e32 v75, v1, v1
	v_max_f32_e32 v76, v5, v5
	v_max_f32_e32 v75, v76, v75
	v_max3_f32 v75, v13, v9, v75
	s_nop 1
	v_mov_b32_dpp v76, v75 quad_perm:[1,0,3,2] row_mask:0xf bank_mask:0xf bound_ctrl:1
	v_max_f32_e32 v76, v76, v76
	v_max_f32_e32 v75, v75, v76
	s_nop 1
	v_mov_b32_dpp v76, v75 quad_perm:[2,3,0,1] row_mask:0xf bank_mask:0xf bound_ctrl:1
	v_max_f32_e32 v76, v76, v76
	v_max_f32_e32 v75, v75, v76
	s_nop 1
	v_mov_b32_dpp v76, v75 row_half_mirror row_mask:0xf bank_mask:0xf bound_ctrl:1
	v_max_f32_e32 v76, v76, v76
	v_max_f32_e32 v75, v75, v76
	s_nop 1
	v_mov_b32_dpp v76, v75 row_ror:8 row_mask:0xf bank_mask:0xf bound_ctrl:1
	s_and_saveexec_b64 s[4:5], vcc
	v_max_f32_e32 v76, v76, v76
	v_max_f32_e32 v75, v75, v75
	v_max_f32_e32 v75, v75, v76
	ds_write_b32 v74, v75 offset:196
	s_or_b64 exec, exec, s[4:5]
	v_max_f32_e32 v75, v2, v2
	v_max_f32_e32 v76, v6, v6
	v_max_f32_e32 v75, v76, v75
	v_max3_f32 v75, v14, v10, v75
	s_nop 1
	v_mov_b32_dpp v76, v75 quad_perm:[1,0,3,2] row_mask:0xf bank_mask:0xf bound_ctrl:1
	v_max_f32_e32 v76, v76, v76
	v_max_f32_e32 v75, v75, v76
	s_nop 1
	v_mov_b32_dpp v76, v75 quad_perm:[2,3,0,1] row_mask:0xf bank_mask:0xf bound_ctrl:1
	v_max_f32_e32 v76, v76, v76
	v_max_f32_e32 v75, v75, v76
	s_nop 1
	v_mov_b32_dpp v76, v75 row_half_mirror row_mask:0xf bank_mask:0xf bound_ctrl:1
	v_max_f32_e32 v76, v76, v76
	v_max_f32_e32 v75, v75, v76
	s_nop 1
	v_mov_b32_dpp v76, v75 row_ror:8 row_mask:0xf bank_mask:0xf bound_ctrl:1
	s_and_saveexec_b64 s[4:5], vcc
	v_max_f32_e32 v76, v76, v76
	v_max_f32_e32 v75, v75, v75
	v_max_f32_e32 v75, v75, v76
	ds_write_b32 v74, v75 offset:200
	s_or_b64 exec, exec, s[4:5]
	v_max_f32_e32 v75, v3, v3
	v_max_f32_e32 v76, v7, v7
	v_max_f32_e32 v75, v76, v75
	v_max3_f32 v75, v15, v11, v75
	s_nop 1
	v_mov_b32_dpp v76, v75 quad_perm:[1,0,3,2] row_mask:0xf bank_mask:0xf bound_ctrl:1
	v_max_f32_e32 v76, v76, v76
	v_max_f32_e32 v75, v75, v76
	s_nop 1
	v_mov_b32_dpp v76, v75 quad_perm:[2,3,0,1] row_mask:0xf bank_mask:0xf bound_ctrl:1
	v_max_f32_e32 v76, v76, v76
	v_max_f32_e32 v75, v75, v76
	s_nop 1
	v_mov_b32_dpp v76, v75 row_half_mirror row_mask:0xf bank_mask:0xf bound_ctrl:1
	v_max_f32_e32 v76, v76, v76
	v_max_f32_e32 v75, v75, v76
	s_nop 1
	v_mov_b32_dpp v76, v75 row_ror:8 row_mask:0xf bank_mask:0xf bound_ctrl:1
	s_and_saveexec_b64 s[4:5], vcc
	v_max_f32_e32 v76, v76, v76
	v_max_f32_e32 v75, v75, v75
	v_max_f32_e32 v75, v75, v76
	ds_write_b32 v74, v75 offset:204
	s_or_b64 exec, exec, s[4:5]
	v_or_b32_e32 v74, 0x11400, v64
	v_or_b32_e32 v75, 0x11500, v64
	v_or_b32_e32 v76, 0x11600, v64
	v_or_b32_e32 v77, 0x11700, v64
	s_waitcnt lgkmcnt(0)
	s_barrier
	ds_read_b32 v76, v76
	ds_read_b32 v77, v77
	ds_read_b32 v74, v74
	ds_read_b32 v75, v75
	v_lshlrev_b32_e32 v78, 1, v112
	s_waitcnt lgkmcnt(3)
	v_max_f32_e32 v76, v76, v76
	s_waitcnt lgkmcnt(2)
	v_max_f32_e32 v77, v77, v77
	v_max_f32_e32 v76, v76, v77
	s_waitcnt lgkmcnt(0)
	v_max3_f32 v74, v74, v75, v76
	v_sub_f32_e32 v60, v60, v74
	v_mul_f32_e32 v60, 0x3d800000, v60
	v_mul_f32_e32 v60, 0x3fb8aa3b, v60
	v_sub_f32_e32 v56, v56, v74
	v_exp_f32_e32 v75, v60
	v_mul_f32_e32 v56, 0x3d800000, v56
	v_sub_f32_e32 v52, v52, v74
	v_mul_f32_e32 v56, 0x3fb8aa3b, v56
	v_mul_f32_e32 v52, 0x3d800000, v52
	v_exp_f32_e32 v56, v56
	v_mul_f32_e32 v52, 0x3fb8aa3b, v52
	v_sub_f32_e32 v48, v48, v74
	v_exp_f32_e32 v52, v52
	v_mul_f32_e32 v48, 0x3d800000, v48
	v_lshl_add_u32 v60, v96, 1, v78
	v_bfe_u32 v78, v75, 16, 1
	v_mul_f32_e32 v48, 0x3fb8aa3b, v48
	v_lshlrev_b32_e32 v113, 2, v73
	v_mad_u32_u24 v73, v73, s83, v60
	v_add_f32_e32 v77, 0, v75
	v_add3_u32 v75, v75, v78, s77
	v_exp_f32_e32 v48, v48
	ds_write_b16_d16_hi v73, v75
	v_add_f32_e32 v75, v56, v77
	v_bfe_u32 v77, v56, 16, 1
	v_add3_u32 v56, v56, v77, s77
	v_bfe_u32 v74, v52, 16, 1
	ds_write_b16_d16_hi v73, v56 offset:32
	v_add_f32_e32 v56, v52, v75
	v_add3_u32 v52, v52, v74, s77
	ds_write_b16_d16_hi v73, v52 offset:64
	v_add_f32_e32 v52, v48, v56
	v_bfe_u32 v56, v48, 16, 1
	v_add3_u32 v48, v48, v56, s77
	ds_write_b16_d16_hi v73, v48 offset:96
	v_lshl_add_u32 v76, v96, 2, v194
	v_add_f32_dpp v48, v52, v52 quad_perm:[1,0,3,2] row_mask:0xf bank_mask:0xf bound_ctrl:1
	s_nop 1
	v_add_f32_dpp v48, v48, v48 quad_perm:[2,3,0,1] row_mask:0xf bank_mask:0xf bound_ctrl:1
	s_nop 1
	v_add_f32_dpp v52, v48, v48 row_half_mirror row_mask:0xf bank_mask:0xf bound_ctrl:1
	v_lshl_add_u32 v48, v113, 2, v76
	s_nop 0
	v_mov_b32_dpp v56, v52 row_ror:8 row_mask:0xf bank_mask:0xf bound_ctrl:1
	s_and_saveexec_b64 s[4:5], vcc
	v_add_f32_e32 v52, v52, v56
	ds_write_b32 v48, v52
	s_or_b64 exec, exec, s[4:5]
	v_or_b32_e32 v52, 1, v113
	v_lshlrev_b32_e32 v56, 2, v52
	v_or_b32_e32 v73, 0x11400, v56
	v_or_b32_e32 v74, 0x11500, v56
	v_or_b32_e32 v75, 0x11600, v56
	v_or_b32_e32 v56, 0x11700, v56
	ds_read_b32 v56, v56
	ds_read_b32 v75, v75
	ds_read_b32 v73, v73
	ds_read_b32 v74, v74
	s_waitcnt lgkmcnt(3)
; __device__ __forceinline__ void xattn_item(const Params& p, char* smem, const int tile, const int hm) {
;     ...
; #pragma unroll
;     for (int m = 0; m < 4; ++m)
; #pragma unroll
;       for (int j = 0; j < 4; ++j) {
;         const int row = m * 16 + lq * 4 + j;
;         const float gmx = fmaxf(fmaxf(sMax[row], sMax[64 + row]), fmaxf(sMax[128 + row], sMax[192 + row]));
;         float sum = 0.f;
; #pragma unroll
;         for (int n = 0; n < 4; ++n) {
;           const float e = __expf((acc[m][n][j] - gmx) * 0.0625f);
;           sum += e;
;           sQ[row * 264 + w * 64 + n * 16 + l15] = f2bf(e);
;         }
;         sum = row16_sum(sum);
;         if (l15 == 0) sSum[w * 64 + row] = sum;
;       }
	v_max_f32_e32 v56, v56, v56
	s_waitcnt lgkmcnt(2)
	v_max_f32_e32 v75, v75, v75
	v_max_f32_e32 v56, v75, v56
	s_waitcnt lgkmcnt(0)
	v_max3_f32 v56, v73, v74, v56
	v_sub_f32_e32 v61, v61, v56
	v_mul_f32_e32 v61, 0x3d800000, v61
	v_mul_f32_e32 v61, 0x3fb8aa3b, v61
	v_sub_f32_e32 v57, v57, v56
	v_exp_f32_e32 v61, v61
	v_mul_f32_e32 v57, 0x3d800000, v57
	v_sub_f32_e32 v53, v53, v56
	v_mul_f32_e32 v57, 0x3fb8aa3b, v57
	v_mul_f32_e32 v53, 0x3d800000, v53
	v_sub_f32_e32 v49, v49, v56
	v_exp_f32_e32 v57, v57
	v_mul_f32_e32 v53, 0x3fb8aa3b, v53
	v_mul_f32_e32 v49, 0x3d800000, v49
	v_exp_f32_e32 v53, v53
	v_mul_f32_e32 v49, 0x3fb8aa3b, v49
	v_bfe_u32 v75, v61, 16, 1
	v_exp_f32_e32 v49, v49
	v_mad_u32_u24 v73, v52, s81, v60
	v_add_f32_e32 v74, 0, v61
	v_add3_u32 v61, v61, v75, s77
	ds_write_b16_d16_hi v73, v61
	v_add_f32_e32 v61, v57, v74
	v_bfe_u32 v74, v57, 16, 1
	v_add3_u32 v57, v57, v74, s77
	v_bfe_u32 v56, v53, 16, 1
	ds_write_b16_d16_hi v73, v57 offset:32
	v_add_f32_e32 v57, v53, v61
	v_add3_u32 v53, v53, v56, s77
	v_bfe_u32 v56, v49, 16, 1
	ds_write_b16_d16_hi v73, v53 offset:64
	v_add_f32_e32 v53, v49, v57
	v_add3_u32 v49, v49, v56, s77
	ds_write_b16_d16_hi v73, v49 offset:96
	s_nop 0
	v_add_f32_dpp v49, v53, v53 quad_perm:[1,0,3,2] row_mask:0xf bank_mask:0xf bound_ctrl:1
	s_nop 1
	v_add_f32_dpp v49, v49, v49 quad_perm:[2,3,0,1] row_mask:0xf bank_mask:0xf bound_ctrl:1
	s_nop 1
	v_add_f32_dpp v49, v49, v49 row_half_mirror row_mask:0xf bank_mask:0xf bound_ctrl:1
	s_nop 1
	v_mov_b32_dpp v53, v49 row_ror:8 row_mask:0xf bank_mask:0xf bound_ctrl:1
	s_and_saveexec_b64 s[4:5], vcc
	v_add_f32_e32 v49, v49, v53
	ds_write_b32 v48, v49 offset:4
	s_or_b64 exec, exec, s[4:5]
	v_lshl_add_u32 v49, v113, 2, v195
	ds_read2st64_b32 v[56:57], v49 offset0:2 offset1:3
	ds_read2st64_b32 v[74:75], v49 offset1:1
	v_mul_u32_u24_e32 v49, 0x210, v52
	v_add_u32_e32 v49, 0x210, v49
	s_waitcnt lgkmcnt(1)
	v_max_f32_e32 v52, v57, v57
	v_max_f32_e32 v53, v56, v56
	v_max_f32_e32 v52, v53, v52
	s_waitcnt lgkmcnt(0)
	v_max3_f32 v52, v74, v75, v52
	v_sub_f32_e32 v53, v62, v52
	v_mul_f32_e32 v53, 0x3d800000, v53
	v_mul_f32_e32 v53, 0x3fb8aa3b, v53
	v_sub_f32_e32 v57, v58, v52
	v_sub_f32_e32 v54, v54, v52
	v_exp_f32_e32 v53, v53
	v_mul_f32_e32 v57, 0x3d800000, v57
	v_mul_f32_e32 v54, 0x3d800000, v54
	v_mul_f32_e32 v57, 0x3fb8aa3b, v57
	v_mul_f32_e32 v54, 0x3fb8aa3b, v54
	v_sub_f32_e32 v50, v50, v52
	v_exp_f32_e32 v57, v57
	v_exp_f32_e32 v54, v54
	v_mul_f32_e32 v50, 0x3d800000, v50
	v_mul_f32_e32 v50, 0x3fb8aa3b, v50
	v_bfe_u32 v61, v53, 16, 1
	v_exp_f32_e32 v50, v50
	v_add_u32_e32 v56, v60, v49
	v_add_f32_e32 v58, 0, v53
	v_add3_u32 v53, v53, v61, s77
	ds_write_b16_d16_hi v56, v53
	v_add_f32_e32 v53, v57, v58
	v_bfe_u32 v52, v54, 16, 1
	v_add_f32_e32 v53, v54, v53
	v_add3_u32 v52, v54, v52, s77
	ds_write_b16_d16_hi v56, v52 offset:64
	v_add_f32_e32 v52, v50, v53
	v_bfe_u32 v53, v50, 16, 1
	v_add3_u32 v50, v50, v53, s77
	ds_write_b16_d16_hi v56, v50 offset:96
	v_bfe_u32 v58, v57, 16, 1
	v_add_f32_dpp v50, v52, v52 quad_perm:[1,0,3,2] row_mask:0xf bank_mask:0xf bound_ctrl:1
	v_add3_u32 v57, v57, v58, s77
	ds_write_b16_d16_hi v56, v57 offset:32
	v_add_f32_dpp v50, v50, v50 quad_perm:[2,3,0,1] row_mask:0xf bank_mask:0xf bound_ctrl:1
	s_nop 1
	v_add_f32_dpp v50, v50, v50 row_half_mirror row_mask:0xf bank_mask:0xf bound_ctrl:1
	s_nop 1
	v_mov_b32_dpp v52, v50 row_ror:8 row_mask:0xf bank_mask:0xf bound_ctrl:1
	s_and_saveexec_b64 s[4:5], vcc
	v_add_f32_e32 v50, v50, v52
	ds_write_b32 v48, v50 offset:8
	s_or_b64 exec, exec, s[4:5]
	v_lshl_add_u32 v50, v113, 2, v196
	ds_read2st64_b32 v[52:53], v50 offset0:2 offset1:3
	ds_read2st64_b32 v[56:57], v50 offset1:1
	v_add_u32_e32 v50, 0x210, v49
	v_add_u32_e32 v49, v60, v50
	s_waitcnt lgkmcnt(1)
	v_max_f32_e32 v53, v53, v53
	v_max_f32_e32 v52, v52, v52
	v_max_f32_e32 v52, v52, v53
	s_waitcnt lgkmcnt(0)
	v_max3_f32 v52, v56, v57, v52
	v_sub_f32_e32 v53, v63, v52
	v_mul_f32_e32 v53, 0x3d800000, v53
	v_mul_f32_e32 v53, 0x3fb8aa3b, v53
	v_sub_f32_e32 v54, v59, v52
	v_sub_f32_e32 v55, v55, v52
	v_exp_f32_e32 v53, v53
	v_mul_f32_e32 v54, 0x3d800000, v54
	v_mul_f32_e32 v55, 0x3d800000, v55
	v_mul_f32_e32 v54, 0x3fb8aa3b, v54
	v_mul_f32_e32 v55, 0x3fb8aa3b, v55
	v_sub_f32_e32 v51, v51, v52
	v_exp_f32_e32 v54, v54
	v_exp_f32_e32 v55, v55
	v_mul_f32_e32 v51, 0x3d800000, v51
	v_mul_f32_e32 v51, 0x3fb8aa3b, v51
	v_bfe_u32 v57, v53, 16, 1
	v_exp_f32_e32 v51, v51
	v_add_f32_e32 v56, 0, v53
	v_add3_u32 v53, v53, v57, s77
	ds_write_b16_d16_hi v49, v53
	v_add_f32_e32 v53, v54, v56
	v_bfe_u32 v52, v55, 16, 1
	v_add_f32_e32 v53, v55, v53
	v_add3_u32 v52, v55, v52, s77
	v_bfe_u32 v56, v54, 16, 1
	ds_write_b16_d16_hi v49, v52 offset:64
	v_add_f32_e32 v52, v51, v53
	v_bfe_u32 v53, v51, 16, 1
	v_add3_u32 v54, v54, v56, s77
	v_add3_u32 v51, v51, v53, s77
	ds_write_b16_d16_hi v49, v54 offset:32
	ds_write_b16_d16_hi v49, v51 offset:96
	v_add_f32_dpp v49, v52, v52 quad_perm:[1,0,3,2] row_mask:0xf bank_mask:0xf bound_ctrl:1
	s_nop 1
	v_add_f32_dpp v49, v49, v49 quad_perm:[2,3,0,1] row_mask:0xf bank_mask:0xf bound_ctrl:1
	s_nop 1
	v_add_f32_dpp v49, v49, v49 row_half_mirror row_mask:0xf bank_mask:0xf bound_ctrl:1
	s_nop 1
	v_mov_b32_dpp v51, v49 row_ror:8 row_mask:0xf bank_mask:0xf bound_ctrl:1
	s_and_saveexec_b64 s[4:5], vcc
	v_add_f32_e32 v49, v49, v51
	ds_write_b32 v48, v49 offset:12
	s_or_b64 exec, exec, s[4:5]
	v_lshlrev_b32_e32 v49, 2, v113
	v_or_b32_e32 v51, 0x11440, v49
	v_or_b32_e32 v52, 0x11540, v49
	v_or_b32_e32 v53, 0x11640, v49
	v_or_b32_e32 v54, 0x11740, v49
	ds_read_b32 v54, v54
	ds_read_b32 v53, v53
	ds_read_b32 v51, v51
	ds_read_b32 v52, v52
	s_waitcnt lgkmcnt(3)
; __device__ __forceinline__ void xattn_item(const Params& p, char* smem, const int tile, const int hm) {
;     ...
; #pragma unroll
;     for (int m = 0; m < 4; ++m)
; #pragma unroll
;       for (int j = 0; j < 4; ++j) {
;         const int row = m * 16 + lq * 4 + j;
;         const float gmx = fmaxf(fmaxf(sMax[row], sMax[64 + row]), fmaxf(sMax[128 + row], sMax[192 + row]));
;         float sum = 0.f;
; #pragma unroll
;         for (int n = 0; n < 4; ++n) {
;           const float e = __expf((acc[m][n][j] - gmx) * 0.0625f);
;           sum += e;
;           sQ[row * 264 + w * 64 + n * 16 + l15] = f2bf(e);
;         }
;         sum = row16_sum(sum);
;         if (l15 == 0) sSum[w * 64 + row] = sum;
;       }
	v_max_f32_e32 v54, v54, v54
	s_waitcnt lgkmcnt(2)
	v_max_f32_e32 v53, v53, v53
	v_max_f32_e32 v53, v53, v54
	s_waitcnt lgkmcnt(0)
	v_max3_f32 v51, v51, v52, v53
	v_sub_f32_e32 v44, v44, v51
	v_mul_f32_e32 v44, 0x3d800000, v44
	v_mul_f32_e32 v44, 0x3fb8aa3b, v44
	v_sub_f32_e32 v40, v40, v51
	v_exp_f32_e32 v52, v44
	v_mul_f32_e32 v40, 0x3d800000, v40
	v_sub_f32_e32 v36, v36, v51
	v_mul_f32_e32 v40, 0x3fb8aa3b, v40
	v_mul_f32_e32 v36, 0x3d800000, v36
	v_exp_f32_e32 v40, v40
	v_mul_f32_e32 v36, 0x3fb8aa3b, v36
	v_sub_f32_e32 v32, v32, v51
	v_exp_f32_e32 v36, v36
	v_mul_f32_e32 v32, 0x3d800000, v32
	v_add_u32_e32 v44, 0x1ad0, v50
	v_bfe_u32 v54, v52, 16, 1
	v_mul_f32_e32 v32, 0x3fb8aa3b, v32
	v_add_u32_e32 v50, v60, v44
	v_add_f32_e32 v53, 0, v52
	v_add3_u32 v52, v52, v54, s77
	v_exp_f32_e32 v32, v32
	ds_write_b16_d16_hi v50, v52
	v_add_f32_e32 v52, v40, v53
	v_bfe_u32 v53, v40, 16, 1
	v_add3_u32 v40, v40, v53, s77
	v_bfe_u32 v51, v36, 16, 1
	ds_write_b16_d16_hi v50, v40 offset:32
	v_add_f32_e32 v40, v36, v52
	v_add3_u32 v36, v36, v51, s77
	ds_write_b16_d16_hi v50, v36 offset:64
	v_add_f32_e32 v36, v32, v40
	v_bfe_u32 v40, v32, 16, 1
	v_add3_u32 v32, v32, v40, s77
	ds_write_b16_d16_hi v50, v32 offset:96
	s_nop 0
	v_add_f32_dpp v32, v36, v36 quad_perm:[1,0,3,2] row_mask:0xf bank_mask:0xf bound_ctrl:1
	s_nop 1
	v_add_f32_dpp v32, v32, v32 quad_perm:[2,3,0,1] row_mask:0xf bank_mask:0xf bound_ctrl:1
	s_nop 1
	v_add_f32_dpp v32, v32, v32 row_half_mirror row_mask:0xf bank_mask:0xf bound_ctrl:1
	s_nop 1
	v_mov_b32_dpp v36, v32 row_ror:8 row_mask:0xf bank_mask:0xf bound_ctrl:1
	s_and_saveexec_b64 s[4:5], vcc
	v_add_f32_e32 v32, v32, v36
	ds_write_b32 v48, v32 offset:64
	s_or_b64 exec, exec, s[4:5]
	v_lshl_add_u32 v32, v113, 2, v206
	ds_read2st64_b32 v[50:51], v32 offset0:2 offset1:3
	ds_read2st64_b32 v[52:53], v32 offset1:1
	v_add_u32_e32 v32, 0x210, v44
	v_add_u32_e32 v36, v60, v32
	s_waitcnt lgkmcnt(1)
	v_max_f32_e32 v40, v51, v51
	v_max_f32_e32 v44, v50, v50
	v_max_f32_e32 v40, v44, v40
	s_waitcnt lgkmcnt(0)
	v_max3_f32 v40, v52, v53, v40
	v_sub_f32_e32 v44, v45, v40
	v_mul_f32_e32 v44, 0x3d800000, v44
	v_mul_f32_e32 v44, 0x3fb8aa3b, v44
	v_sub_f32_e32 v41, v41, v40
	v_exp_f32_e32 v44, v44
	v_mul_f32_e32 v41, 0x3d800000, v41
	v_sub_f32_e32 v37, v37, v40
	v_mul_f32_e32 v41, 0x3fb8aa3b, v41
	v_mul_f32_e32 v37, 0x3d800000, v37
	v_sub_f32_e32 v33, v33, v40
	v_exp_f32_e32 v41, v41
	v_mul_f32_e32 v37, 0x3fb8aa3b, v37
	v_mul_f32_e32 v33, 0x3d800000, v33
	v_exp_f32_e32 v37, v37
	v_mul_f32_e32 v33, 0x3fb8aa3b, v33
	v_bfe_u32 v50, v44, 16, 1
	v_exp_f32_e32 v33, v33
	v_add_f32_e32 v45, 0, v44
	v_add3_u32 v44, v44, v50, s77
	ds_write_b16_d16_hi v36, v44
	v_add_f32_e32 v44, v41, v45
	v_bfe_u32 v45, v41, 16, 1
	v_add3_u32 v41, v41, v45, s77
	v_bfe_u32 v40, v37, 16, 1
	ds_write_b16_d16_hi v36, v41 offset:32
	v_add_f32_e32 v41, v37, v44
	v_add3_u32 v37, v37, v40, s77
	v_bfe_u32 v40, v33, 16, 1
	ds_write_b16_d16_hi v36, v37 offset:64
	v_add_f32_e32 v37, v33, v41
	v_add3_u32 v33, v33, v40, s77
	ds_write_b16_d16_hi v36, v33 offset:96
	s_nop 0
	v_add_f32_dpp v33, v37, v37 quad_perm:[1,0,3,2] row_mask:0xf bank_mask:0xf bound_ctrl:1
	s_nop 1
	v_add_f32_dpp v33, v33, v33 quad_perm:[2,3,0,1] row_mask:0xf bank_mask:0xf bound_ctrl:1
	s_nop 1
	v_add_f32_dpp v33, v33, v33 row_half_mirror row_mask:0xf bank_mask:0xf bound_ctrl:1
	s_nop 1
	v_mov_b32_dpp v36, v33 row_ror:8 row_mask:0xf bank_mask:0xf bound_ctrl:1
	s_and_saveexec_b64 s[4:5], vcc
	v_add_f32_e32 v33, v33, v36
	ds_write_b32 v48, v33 offset:68
	s_or_b64 exec, exec, s[4:5]
	v_lshl_add_u32 v33, v113, 2, v130
	ds_read2st64_b32 v[36:37], v33 offset0:2 offset1:3
	ds_read2st64_b32 v[40:41], v33 offset1:1
	v_add_u32_e32 v32, 0x210, v32
	v_add_u32_e32 v32, v60, v32
	s_waitcnt lgkmcnt(1)
	v_max_f32_e32 v33, v37, v37
	v_max_f32_e32 v36, v36, v36
	v_max_f32_e32 v33, v36, v33
	s_waitcnt lgkmcnt(0)
	v_max3_f32 v33, v40, v41, v33
	v_sub_f32_e32 v36, v46, v33
	v_mul_f32_e32 v36, 0x3d800000, v36
	v_mul_f32_e32 v36, 0x3fb8aa3b, v36
	v_sub_f32_e32 v37, v42, v33
	v_sub_f32_e32 v38, v38, v33
	v_exp_f32_e32 v36, v36
	v_mul_f32_e32 v37, 0x3d800000, v37
	v_mul_f32_e32 v38, 0x3d800000, v38
	v_mul_f32_e32 v37, 0x3fb8aa3b, v37
	v_mul_f32_e32 v38, 0x3fb8aa3b, v38
	v_sub_f32_e32 v33, v34, v33
	v_exp_f32_e32 v37, v37
	v_exp_f32_e32 v38, v38
	v_mul_f32_e32 v33, 0x3d800000, v33
	v_mul_f32_e32 v33, 0x3fb8aa3b, v33
	v_bfe_u32 v41, v36, 16, 1
	v_exp_f32_e32 v33, v33
	v_add_f32_e32 v40, 0, v36
	v_add3_u32 v36, v36, v41, s77
	ds_write_b16_d16_hi v32, v36
	v_add_f32_e32 v36, v37, v40
	v_bfe_u32 v34, v38, 16, 1
	v_add_f32_e32 v36, v38, v36
	v_add3_u32 v34, v38, v34, s77
	ds_write_b16_d16_hi v32, v34 offset:64
	v_add_f32_e32 v34, v33, v36
	v_bfe_u32 v36, v33, 16, 1
	v_add3_u32 v33, v33, v36, s77
	ds_write_b16_d16_hi v32, v33 offset:96
	v_bfe_u32 v40, v37, 16, 1
	v_add_f32_dpp v33, v34, v34 quad_perm:[1,0,3,2] row_mask:0xf bank_mask:0xf bound_ctrl:1
	v_add3_u32 v37, v37, v40, s77
	ds_write_b16_d16_hi v32, v37 offset:32
	v_add_f32_dpp v33, v33, v33 quad_perm:[2,3,0,1] row_mask:0xf bank_mask:0xf bound_ctrl:1
	s_nop 1
	v_add_f32_dpp v33, v33, v33 row_half_mirror row_mask:0xf bank_mask:0xf bound_ctrl:1
	s_nop 1
	v_mov_b32_dpp v34, v33 row_ror:8 row_mask:0xf bank_mask:0xf bound_ctrl:1
	s_and_saveexec_b64 s[4:5], vcc
	v_add_f32_e32 v33, v33, v34
	ds_write_b32 v48, v33 offset:72
	s_or_b64 exec, exec, s[4:5]
	v_lshl_add_u32 v33, v113, 2, v131
	ds_read2st64_b32 v[36:37], v33 offset0:2 offset1:3
	ds_read2st64_b32 v[40:41], v33 offset1:1
	s_waitcnt lgkmcnt(1)
	v_max_f32_e32 v33, v37, v37
	v_max_f32_e32 v34, v36, v36
	v_max_f32_e32 v33, v34, v33
	s_waitcnt lgkmcnt(0)
; __device__ __forceinline__ void xattn_item(const Params& p, char* smem, const int tile, const int hm) {
;     ...
; #pragma unroll
;     for (int m = 0; m < 4; ++m)
; #pragma unroll
;       for (int j = 0; j < 4; ++j) {
;         const int row = m * 16 + lq * 4 + j;
;         const float gmx = fmaxf(fmaxf(sMax[row], sMax[64 + row]), fmaxf(sMax[128 + row], sMax[192 + row]));
;         float sum = 0.f;
; #pragma unroll
;         for (int n = 0; n < 4; ++n) {
;           const float e = __expf((acc[m][n][j] - gmx) * 0.0625f);
;           sum += e;
;           sQ[row * 264 + w * 64 + n * 16 + l15] = f2bf(e);
;         }
;         sum = row16_sum(sum);
;         if (l15 == 0) sSum[w * 64 + row] = sum;
;       }
	v_max3_f32 v33, v40, v41, v33
	v_sub_f32_e32 v34, v47, v33
	v_mul_f32_e32 v34, 0x3d800000, v34
	v_sub_f32_e32 v36, v43, v33
	v_mul_f32_e32 v34, 0x3fb8aa3b, v34
	v_exp_f32_e32 v34, v34
	v_mul_f32_e32 v36, 0x3d800000, v36
	v_mul_f32_e32 v36, 0x3fb8aa3b, v36
	v_exp_f32_e32 v36, v36
	v_bfe_u32 v38, v34, 16, 1
	v_add_f32_e32 v37, 0, v34
	v_add3_u32 v34, v34, v38, s77
	ds_write_b16_d16_hi v32, v34 offset:528
	v_add_f32_e32 v34, v36, v37
	v_sub_f32_e32 v37, v39, v33
	v_mul_f32_e32 v37, 0x3d800000, v37
	v_mul_f32_e32 v37, 0x3fb8aa3b, v37
	v_sub_f32_e32 v33, v35, v33
	v_exp_f32_e32 v37, v37
	v_mul_f32_e32 v33, 0x3d800000, v33
	v_mul_f32_e32 v33, 0x3fb8aa3b, v33
	v_exp_f32_e32 v33, v33
	v_bfe_u32 v35, v37, 16, 1
	v_add3_u32 v35, v37, v35, s77
	v_add_f32_e32 v34, v37, v34
	ds_write_b16_d16_hi v32, v35 offset:592
	v_bfe_u32 v35, v33, 16, 1
	v_add_f32_e32 v34, v33, v34
	v_add3_u32 v33, v33, v35, s77
	ds_write_b16_d16_hi v32, v33 offset:624
	v_bfe_u32 v38, v36, 16, 1
	v_add_f32_dpp v33, v34, v34 quad_perm:[1,0,3,2] row_mask:0xf bank_mask:0xf bound_ctrl:1
	v_add3_u32 v36, v36, v38, s77
	ds_write_b16_d16_hi v32, v36 offset:560
	v_add_f32_dpp v33, v33, v33 quad_perm:[2,3,0,1] row_mask:0xf bank_mask:0xf bound_ctrl:1
	s_nop 1
	v_add_f32_dpp v33, v33, v33 row_half_mirror row_mask:0xf bank_mask:0xf bound_ctrl:1
	s_nop 1
	v_mov_b32_dpp v34, v33 row_ror:8 row_mask:0xf bank_mask:0xf bound_ctrl:1
	s_and_saveexec_b64 s[4:5], vcc
	v_add_f32_e32 v33, v33, v34
	ds_write_b32 v48, v33 offset:76
	s_or_b64 exec, exec, s[4:5]
	v_or_b32_e32 v33, 0x11480, v49
	v_or_b32_e32 v34, 0x11580, v49
	v_or_b32_e32 v35, 0x11680, v49
	v_or_b32_e32 v36, 0x11780, v49
	ds_read_b32 v36, v36
	ds_read_b32 v35, v35
	ds_read_b32 v33, v33
	ds_read_b32 v34, v34
	s_waitcnt lgkmcnt(3)
	v_max_f32_e32 v36, v36, v36
	s_waitcnt lgkmcnt(2)
	v_max_f32_e32 v35, v35, v35
	v_max_f32_e32 v35, v35, v36
	s_waitcnt lgkmcnt(0)
	v_max3_f32 v33, v33, v34, v35
	v_sub_f32_e32 v28, v28, v33
	v_mul_f32_e32 v28, 0x3d800000, v28
	v_mul_f32_e32 v28, 0x3fb8aa3b, v28
	v_sub_f32_e32 v24, v24, v33
	v_exp_f32_e32 v28, v28
	v_mul_f32_e32 v24, 0x3d800000, v24
	v_mul_f32_e32 v24, 0x3fb8aa3b, v24
	v_sub_f32_e32 v20, v20, v33
	v_exp_f32_e32 v24, v24
	v_mul_f32_e32 v20, 0x3d800000, v20
	v_mul_f32_e32 v20, 0x3fb8aa3b, v20
	v_sub_f32_e32 v16, v16, v33
	v_bfe_u32 v35, v28, 16, 1
	v_exp_f32_e32 v20, v20
	v_mul_f32_e32 v16, 0x3d800000, v16
	v_add_f32_e32 v34, 0, v28
	v_add3_u32 v28, v28, v35, s77
	v_mul_f32_e32 v16, 0x3fb8aa3b, v16
	ds_write_b16_d16_hi v32, v28 offset:7392
	v_add_f32_e32 v28, v24, v34
	v_bfe_u32 v34, v24, 16, 1
	v_exp_f32_e32 v16, v16
	v_add3_u32 v24, v24, v34, s77
	ds_write_b16_d16_hi v32, v24 offset:7424
	v_add_f32_e32 v24, v20, v28
	v_bfe_u32 v28, v20, 16, 1
	v_add3_u32 v20, v20, v28, s77
	ds_write_b16_d16_hi v32, v20 offset:7456
	v_add_f32_e32 v20, v16, v24
	v_bfe_u32 v24, v16, 16, 1
	v_add3_u32 v16, v16, v24, s77
	ds_write_b16_d16_hi v32, v16 offset:7488
	s_nop 0
	v_add_f32_dpp v16, v20, v20 quad_perm:[1,0,3,2] row_mask:0xf bank_mask:0xf bound_ctrl:1
	s_nop 1
	v_add_f32_dpp v16, v16, v16 quad_perm:[2,3,0,1] row_mask:0xf bank_mask:0xf bound_ctrl:1
	s_nop 1
	v_add_f32_dpp v16, v16, v16 row_half_mirror row_mask:0xf bank_mask:0xf bound_ctrl:1
	s_nop 1
	v_mov_b32_dpp v20, v16 row_ror:8 row_mask:0xf bank_mask:0xf bound_ctrl:1
	s_and_saveexec_b64 s[4:5], vcc
	v_add_f32_e32 v16, v16, v20
	ds_write_b32 v48, v16 offset:128
	s_or_b64 exec, exec, s[4:5]
	v_lshl_add_u32 v16, v113, 2, v132
	ds_read2st64_b32 v[34:35], v16 offset0:2 offset1:3
	ds_read2st64_b32 v[36:37], v16 offset1:1
	s_waitcnt lgkmcnt(1)
	v_max_f32_e32 v16, v35, v35
	v_max_f32_e32 v20, v34, v34
	v_max_f32_e32 v16, v20, v16
	s_waitcnt lgkmcnt(0)
	v_max3_f32 v16, v36, v37, v16
	v_sub_f32_e32 v20, v29, v16
	v_mul_f32_e32 v20, 0x3d800000, v20
	v_sub_f32_e32 v24, v25, v16
	v_mul_f32_e32 v20, 0x3fb8aa3b, v20
	v_sub_f32_e32 v21, v21, v16
	v_exp_f32_e32 v20, v20
	v_mul_f32_e32 v24, 0x3d800000, v24
	v_mul_f32_e32 v21, 0x3d800000, v21
	v_mul_f32_e32 v24, 0x3fb8aa3b, v24
	v_mul_f32_e32 v21, 0x3fb8aa3b, v21
	v_sub_f32_e32 v16, v17, v16
	v_exp_f32_e32 v24, v24
	v_exp_f32_e32 v21, v21
	v_mul_f32_e32 v16, 0x3d800000, v16
	v_mul_f32_e32 v16, 0x3fb8aa3b, v16
	v_bfe_u32 v28, v20, 16, 1
	v_exp_f32_e32 v16, v16
	v_add_f32_e32 v25, 0, v20
	v_add3_u32 v20, v20, v28, s77
	ds_write_b16_d16_hi v32, v20 offset:7920
	v_add_f32_e32 v20, v24, v25
	v_bfe_u32 v17, v21, 16, 1
	v_add_f32_e32 v20, v21, v20
	v_add3_u32 v17, v21, v17, s77
	ds_write_b16_d16_hi v32, v17 offset:7984
	v_add_f32_e32 v17, v16, v20
	v_bfe_u32 v20, v16, 16, 1
	v_add3_u32 v16, v16, v20, s77
	ds_write_b16_d16_hi v32, v16 offset:8016
	v_bfe_u32 v25, v24, 16, 1
	v_add_f32_dpp v16, v17, v17 quad_perm:[1,0,3,2] row_mask:0xf bank_mask:0xf bound_ctrl:1
	v_add3_u32 v24, v24, v25, s77
	ds_write_b16_d16_hi v32, v24 offset:7952
	v_add_f32_dpp v16, v16, v16 quad_perm:[2,3,0,1] row_mask:0xf bank_mask:0xf bound_ctrl:1
	s_nop 1
	v_add_f32_dpp v16, v16, v16 row_half_mirror row_mask:0xf bank_mask:0xf bound_ctrl:1
	s_nop 1
	v_mov_b32_dpp v17, v16 row_ror:8 row_mask:0xf bank_mask:0xf bound_ctrl:1
	s_and_saveexec_b64 s[4:5], vcc
	v_add_f32_e32 v16, v16, v17
	ds_write_b32 v48, v16 offset:132
	s_or_b64 exec, exec, s[4:5]
	v_lshl_add_u32 v20, v113, 2, v133
	ds_read2st64_b32 v[16:17], v20 offset0:2 offset1:3
	ds_read2st64_b32 v[20:21], v20 offset1:1
	s_waitcnt lgkmcnt(1)
	v_max_f32_e32 v17, v17, v17
	v_max_f32_e32 v16, v16, v16
	v_max_f32_e32 v16, v16, v17
	s_waitcnt lgkmcnt(0)
; __device__ __forceinline__ void xattn_item(const Params& p, char* smem, const int tile, const int hm) {
;     ...
; #pragma unroll
;     for (int m = 0; m < 4; ++m)
; #pragma unroll
;       for (int j = 0; j < 4; ++j) {
;         const int row = m * 16 + lq * 4 + j;
;         const float gmx = fmaxf(fmaxf(sMax[row], sMax[64 + row]), fmaxf(sMax[128 + row], sMax[192 + row]));
;         float sum = 0.f;
; #pragma unroll
;         for (int n = 0; n < 4; ++n) {
;           const float e = __expf((acc[m][n][j] - gmx) * 0.0625f);
;           sum += e;
;           sQ[row * 264 + w * 64 + n * 16 + l15] = f2bf(e);
;         }
;         sum = row16_sum(sum);
;         if (l15 == 0) sSum[w * 64 + row] = sum;
;       }
	v_max3_f32 v16, v20, v21, v16
	v_sub_f32_e32 v17, v30, v16
	v_mul_f32_e32 v17, 0x3d800000, v17
	v_sub_f32_e32 v20, v26, v16
	v_mul_f32_e32 v17, 0x3fb8aa3b, v17
	v_exp_f32_e32 v17, v17
	v_mul_f32_e32 v20, 0x3d800000, v20
	v_mul_f32_e32 v20, 0x3fb8aa3b, v20
	v_exp_f32_e32 v20, v20
	v_bfe_u32 v24, v17, 16, 1
	v_add_f32_e32 v21, 0, v17
	v_add3_u32 v17, v17, v24, s77
	ds_write_b16_d16_hi v32, v17 offset:8448
	v_add_f32_e32 v17, v20, v21
	v_sub_f32_e32 v21, v22, v16
	v_mul_f32_e32 v21, 0x3d800000, v21
	v_mul_f32_e32 v21, 0x3fb8aa3b, v21
	v_sub_f32_e32 v16, v18, v16
	v_exp_f32_e32 v21, v21
	v_mul_f32_e32 v16, 0x3d800000, v16
	v_mul_f32_e32 v16, 0x3fb8aa3b, v16
	v_exp_f32_e32 v16, v16
	v_bfe_u32 v18, v21, 16, 1
	v_add3_u32 v18, v21, v18, s77
	v_add_f32_e32 v17, v21, v17
	ds_write_b16_d16_hi v32, v18 offset:8512
	v_bfe_u32 v18, v16, 16, 1
	v_add_f32_e32 v17, v16, v17
	v_add3_u32 v16, v16, v18, s77
	ds_write_b16_d16_hi v32, v16 offset:8544
	v_bfe_u32 v22, v20, 16, 1
	v_add_f32_dpp v16, v17, v17 quad_perm:[1,0,3,2] row_mask:0xf bank_mask:0xf bound_ctrl:1
	v_add3_u32 v20, v20, v22, s77
	ds_write_b16_d16_hi v32, v20 offset:8480
	v_add_f32_dpp v16, v16, v16 quad_perm:[2,3,0,1] row_mask:0xf bank_mask:0xf bound_ctrl:1
	s_nop 1
	v_add_f32_dpp v16, v16, v16 row_half_mirror row_mask:0xf bank_mask:0xf bound_ctrl:1
	s_nop 1
	v_mov_b32_dpp v17, v16 row_ror:8 row_mask:0xf bank_mask:0xf bound_ctrl:1
	s_and_saveexec_b64 s[4:5], vcc
	v_add_f32_e32 v16, v16, v17
	ds_write_b32 v48, v16 offset:136
	s_or_b64 exec, exec, s[4:5]
	v_lshl_add_u32 v18, v113, 2, v134
	ds_read2st64_b32 v[16:17], v18 offset0:2 offset1:3
	ds_read2st64_b32 v[20:21], v18 offset1:1
	s_waitcnt lgkmcnt(1)
	v_max_f32_e32 v17, v17, v17
	v_max_f32_e32 v16, v16, v16
	v_max_f32_e32 v16, v16, v17
	s_waitcnt lgkmcnt(0)
	v_max3_f32 v16, v20, v21, v16
	v_sub_f32_e32 v17, v31, v16
	v_mul_f32_e32 v17, 0x3d800000, v17
	v_sub_f32_e32 v18, v27, v16
	v_mul_f32_e32 v17, 0x3fb8aa3b, v17
	v_exp_f32_e32 v17, v17
	v_mul_f32_e32 v18, 0x3d800000, v18
	v_mul_f32_e32 v18, 0x3fb8aa3b, v18
	v_exp_f32_e32 v18, v18
	v_bfe_u32 v21, v17, 16, 1
	v_add_f32_e32 v20, 0, v17
	v_add3_u32 v17, v17, v21, s77
	ds_write_b16_d16_hi v32, v17 offset:8976
	v_add_f32_e32 v17, v18, v20
	v_sub_f32_e32 v20, v23, v16
	v_mul_f32_e32 v20, 0x3d800000, v20
	v_mul_f32_e32 v20, 0x3fb8aa3b, v20
	v_sub_f32_e32 v16, v19, v16
	v_exp_f32_e32 v20, v20
	v_mul_f32_e32 v16, 0x3d800000, v16
	v_mul_f32_e32 v16, 0x3fb8aa3b, v16
	v_bfe_u32 v21, v18, 16, 1
	v_exp_f32_e32 v16, v16
	v_add3_u32 v18, v18, v21, s77
	ds_write_b16_d16_hi v32, v18 offset:9008
	v_bfe_u32 v18, v20, 16, 1
	v_add3_u32 v18, v20, v18, s77
	v_add_f32_e32 v17, v20, v17
	ds_write_b16_d16_hi v32, v18 offset:9040
	v_bfe_u32 v18, v16, 16, 1
	v_add_f32_e32 v17, v16, v17
	v_add3_u32 v16, v16, v18, s77
	ds_write_b16_d16_hi v32, v16 offset:9072
	s_nop 0
	v_add_f32_dpp v16, v17, v17 quad_perm:[1,0,3,2] row_mask:0xf bank_mask:0xf bound_ctrl:1
	s_nop 1
	v_add_f32_dpp v16, v16, v16 quad_perm:[2,3,0,1] row_mask:0xf bank_mask:0xf bound_ctrl:1
	s_nop 1
	v_add_f32_dpp v16, v16, v16 row_half_mirror row_mask:0xf bank_mask:0xf bound_ctrl:1
	s_nop 1
	v_mov_b32_dpp v17, v16 row_ror:8 row_mask:0xf bank_mask:0xf bound_ctrl:1
	s_and_saveexec_b64 s[4:5], vcc
	v_add_f32_e32 v16, v16, v17
	ds_write_b32 v48, v16 offset:140
	s_or_b64 exec, exec, s[4:5]
	v_or_b32_e32 v16, 0x114c0, v49
	v_or_b32_e32 v17, 0x115c0, v49
	v_or_b32_e32 v18, 0x116c0, v49
	v_or_b32_e32 v19, 0x117c0, v49
	ds_read_b32 v19, v19
	ds_read_b32 v18, v18
	ds_read_b32 v16, v16
	ds_read_b32 v17, v17
	s_waitcnt lgkmcnt(3)
	v_max_f32_e32 v19, v19, v19
	s_waitcnt lgkmcnt(2)
	v_max_f32_e32 v18, v18, v18
	v_max_f32_e32 v18, v18, v19
	s_waitcnt lgkmcnt(0)
	v_max3_f32 v16, v16, v17, v18
	v_sub_f32_e32 v12, v12, v16
	v_mul_f32_e32 v12, 0x3d800000, v12
	v_mul_f32_e32 v12, 0x3fb8aa3b, v12
	v_sub_f32_e32 v8, v8, v16
	v_exp_f32_e32 v12, v12
	v_mul_f32_e32 v8, 0x3d800000, v8
	v_mul_f32_e32 v8, 0x3fb8aa3b, v8
	v_sub_f32_e32 v4, v4, v16
	v_exp_f32_e32 v8, v8
	v_mul_f32_e32 v4, 0x3d800000, v4
	v_mul_f32_e32 v4, 0x3fb8aa3b, v4
	v_sub_f32_e32 v0, v0, v16
	v_bfe_u32 v18, v12, 16, 1
	v_exp_f32_e32 v4, v4
	v_mul_f32_e32 v0, 0x3d800000, v0
	v_add_f32_e32 v17, 0, v12
	v_add3_u32 v12, v12, v18, s77
	v_mul_f32_e32 v0, 0x3fb8aa3b, v0
	ds_write_b16_d16_hi v32, v12 offset:15840
	v_add_f32_e32 v12, v8, v17
	v_bfe_u32 v17, v8, 16, 1
	v_exp_f32_e32 v0, v0
	v_add3_u32 v8, v8, v17, s77
	ds_write_b16_d16_hi v32, v8 offset:15872
	v_add_f32_e32 v8, v4, v12
	v_bfe_u32 v12, v4, 16, 1
	v_add3_u32 v4, v4, v12, s77
	ds_write_b16_d16_hi v32, v4 offset:15904
	v_add_f32_e32 v4, v0, v8
	v_bfe_u32 v8, v0, 16, 1
	v_add3_u32 v0, v0, v8, s77
	ds_write_b16_d16_hi v32, v0 offset:15936
	s_nop 0
	v_add_f32_dpp v0, v4, v4 quad_perm:[1,0,3,2] row_mask:0xf bank_mask:0xf bound_ctrl:1
	s_nop 1
	v_add_f32_dpp v0, v0, v0 quad_perm:[2,3,0,1] row_mask:0xf bank_mask:0xf bound_ctrl:1
	s_nop 1
	v_add_f32_dpp v0, v0, v0 row_half_mirror row_mask:0xf bank_mask:0xf bound_ctrl:1
	s_nop 1
	v_mov_b32_dpp v4, v0 row_ror:8 row_mask:0xf bank_mask:0xf bound_ctrl:1
	s_and_saveexec_b64 s[4:5], vcc
	v_add_f32_e32 v0, v0, v4
	ds_write_b32 v48, v0 offset:192
	s_or_b64 exec, exec, s[4:5]
	v_lshl_add_u32 v0, v113, 2, v135
	ds_read2st64_b32 v[16:17], v0 offset0:2 offset1:3
	ds_read2st64_b32 v[18:19], v0 offset1:1
	s_waitcnt lgkmcnt(1)
	v_max_f32_e32 v0, v17, v17
	v_max_f32_e32 v4, v16, v16
	v_max_f32_e32 v0, v4, v0
	s_waitcnt lgkmcnt(0)
; __device__ __forceinline__ void xattn_item(const Params& p, char* smem, const int tile, const int hm) {
;     ...
; #pragma unroll
;     for (int m = 0; m < 4; ++m)
; #pragma unroll
;       for (int j = 0; j < 4; ++j) {
;         const int row = m * 16 + lq * 4 + j;
;         const float gmx = fmaxf(fmaxf(sMax[row], sMax[64 + row]), fmaxf(sMax[128 + row], sMax[192 + row]));
;         float sum = 0.f;
; #pragma unroll
;         for (int n = 0; n < 4; ++n) {
;           const float e = __expf((acc[m][n][j] - gmx) * 0.0625f);
;           sum += e;
;           sQ[row * 264 + w * 64 + n * 16 + l15] = f2bf(e);
;         }
;         sum = row16_sum(sum);
;         if (l15 == 0) sSum[w * 64 + row] = sum;
;       }
; #pragma unroll
;     for (int m = 0; m < 4; ++m)
; #pragma unroll
;       for (int n = 0; n < 4; ++n) acc[m][n] = f32x4{0.f, 0.f, 0.f, 0.f};
;     for (int kt = 0; kt < 4; ++kt) {
; #pragma unroll
;       for (int i = 0; i < 8; ++i) {
;         const int c = tid + 256 * i, row = c >> 3, cc = c & 7;
;         st[i] = *(const u32x4*)(vtm + (size_t)(b * 1024 + hm * 256 + row) * 256 + kt * 64 + cc * 8);
;       }
	v_max3_f32 v0, v18, v19, v0
	v_sub_f32_e32 v4, v13, v0
	v_mul_f32_e32 v4, 0x3d800000, v4
	v_sub_f32_e32 v8, v9, v0
	v_mul_f32_e32 v4, 0x3fb8aa3b, v4
	v_sub_f32_e32 v5, v5, v0
	v_exp_f32_e32 v4, v4
	v_mul_f32_e32 v8, 0x3d800000, v8
	v_mul_f32_e32 v5, 0x3d800000, v5
	v_mul_f32_e32 v8, 0x3fb8aa3b, v8
	v_mul_f32_e32 v5, 0x3fb8aa3b, v5
	v_sub_f32_e32 v0, v1, v0
	v_exp_f32_e32 v8, v8
	v_exp_f32_e32 v5, v5
	v_mul_f32_e32 v0, 0x3d800000, v0
	v_mul_f32_e32 v0, 0x3fb8aa3b, v0
	v_bfe_u32 v12, v4, 16, 1
	v_exp_f32_e32 v0, v0
	v_add_f32_e32 v9, 0, v4
	v_add3_u32 v4, v4, v12, s77
	ds_write_b16_d16_hi v32, v4 offset:16368
	v_add_f32_e32 v4, v8, v9
	v_bfe_u32 v1, v5, 16, 1
	v_add_f32_e32 v4, v5, v4
	v_add3_u32 v1, v5, v1, s77
	ds_write_b16_d16_hi v32, v1 offset:16432
	v_add_f32_e32 v1, v0, v4
	v_bfe_u32 v4, v0, 16, 1
	v_add3_u32 v0, v0, v4, s77
	ds_write_b16_d16_hi v32, v0 offset:16464
	v_bfe_u32 v9, v8, 16, 1
	v_add_f32_dpp v0, v1, v1 quad_perm:[1,0,3,2] row_mask:0xf bank_mask:0xf bound_ctrl:1
	v_add3_u32 v8, v8, v9, s77
	ds_write_b16_d16_hi v32, v8 offset:16400
	v_add_f32_dpp v0, v0, v0 quad_perm:[2,3,0,1] row_mask:0xf bank_mask:0xf bound_ctrl:1
	s_nop 1
	v_add_f32_dpp v0, v0, v0 row_half_mirror row_mask:0xf bank_mask:0xf bound_ctrl:1
	s_nop 1
	v_mov_b32_dpp v1, v0 row_ror:8 row_mask:0xf bank_mask:0xf bound_ctrl:1
	s_and_saveexec_b64 s[4:5], vcc
	v_add_f32_e32 v0, v0, v1
	ds_write_b32 v48, v0 offset:196
	s_or_b64 exec, exec, s[4:5]
	v_lshl_add_u32 v4, v113, 2, v136
	ds_read2st64_b32 v[0:1], v4 offset0:2 offset1:3
	ds_read2st64_b32 v[4:5], v4 offset1:1
	s_waitcnt lgkmcnt(1)
	v_max_f32_e32 v1, v1, v1
	v_max_f32_e32 v0, v0, v0
	v_max_f32_e32 v0, v0, v1
	s_waitcnt lgkmcnt(0)
	v_max3_f32 v0, v4, v5, v0
	v_sub_f32_e32 v1, v14, v0
	v_mul_f32_e32 v1, 0x3d800000, v1
	v_sub_f32_e32 v4, v10, v0
	v_mul_f32_e32 v1, 0x3fb8aa3b, v1
	v_exp_f32_e32 v1, v1
	v_mul_f32_e32 v4, 0x3d800000, v4
	v_mul_f32_e32 v4, 0x3fb8aa3b, v4
	v_exp_f32_e32 v4, v4
	v_bfe_u32 v8, v1, 16, 1
	v_add_f32_e32 v5, 0, v1
	v_add3_u32 v1, v1, v8, s77
	ds_write_b16_d16_hi v32, v1 offset:16896
	v_add_f32_e32 v1, v4, v5
	v_sub_f32_e32 v5, v6, v0
	v_mul_f32_e32 v5, 0x3d800000, v5
	v_mul_f32_e32 v5, 0x3fb8aa3b, v5
	v_sub_f32_e32 v0, v2, v0
	v_exp_f32_e32 v5, v5
	v_mul_f32_e32 v0, 0x3d800000, v0
	v_mul_f32_e32 v0, 0x3fb8aa3b, v0
	v_exp_f32_e32 v0, v0
	v_bfe_u32 v2, v5, 16, 1
	v_add3_u32 v2, v5, v2, s77
	v_add_f32_e32 v1, v5, v1
	ds_write_b16_d16_hi v32, v2 offset:16960
	v_bfe_u32 v2, v0, 16, 1
	v_add_f32_e32 v1, v0, v1
	v_add3_u32 v0, v0, v2, s77
	ds_write_b16_d16_hi v32, v0 offset:16992
	v_bfe_u32 v6, v4, 16, 1
	v_add_f32_dpp v0, v1, v1 quad_perm:[1,0,3,2] row_mask:0xf bank_mask:0xf bound_ctrl:1
	v_add3_u32 v4, v4, v6, s77
	ds_write_b16_d16_hi v32, v4 offset:16928
	v_add_f32_dpp v0, v0, v0 quad_perm:[2,3,0,1] row_mask:0xf bank_mask:0xf bound_ctrl:1
	s_nop 1
	v_add_f32_dpp v0, v0, v0 row_half_mirror row_mask:0xf bank_mask:0xf bound_ctrl:1
	s_nop 1
	v_mov_b32_dpp v1, v0 row_ror:8 row_mask:0xf bank_mask:0xf bound_ctrl:1
	s_and_saveexec_b64 s[4:5], vcc
	v_add_f32_e32 v0, v0, v1
	ds_write_b32 v48, v0 offset:200
	s_or_b64 exec, exec, s[4:5]
	v_lshl_add_u32 v2, v113, 2, v137
	ds_read2st64_b32 v[0:1], v2 offset0:2 offset1:3
	ds_read2st64_b32 v[4:5], v2 offset1:1
	s_waitcnt lgkmcnt(1)
	v_max_f32_e32 v1, v1, v1
	v_max_f32_e32 v0, v0, v0
	v_max_f32_e32 v0, v0, v1
	s_waitcnt lgkmcnt(0)
	v_max3_f32 v0, v4, v5, v0
	v_sub_f32_e32 v1, v15, v0
	v_mul_f32_e32 v1, 0x3d800000, v1
	v_sub_f32_e32 v2, v11, v0
	v_mul_f32_e32 v1, 0x3fb8aa3b, v1
	v_exp_f32_e32 v1, v1
	v_mul_f32_e32 v2, 0x3d800000, v2
	v_mul_f32_e32 v2, 0x3fb8aa3b, v2
	v_exp_f32_e32 v2, v2
	v_bfe_u32 v5, v1, 16, 1
	v_add_f32_e32 v4, 0, v1
	v_add3_u32 v1, v1, v5, s77
	ds_write_b16_d16_hi v32, v1 offset:17424
	v_add_f32_e32 v1, v2, v4
	v_sub_f32_e32 v4, v7, v0
	v_mul_f32_e32 v4, 0x3d800000, v4
	v_mul_f32_e32 v4, 0x3fb8aa3b, v4
	v_sub_f32_e32 v0, v3, v0
	v_exp_f32_e32 v4, v4
	v_mul_f32_e32 v0, 0x3d800000, v0
	v_mul_f32_e32 v0, 0x3fb8aa3b, v0
	v_bfe_u32 v5, v2, 16, 1
	v_exp_f32_e32 v0, v0
	v_add3_u32 v2, v2, v5, s77
	ds_write_b16_d16_hi v32, v2 offset:17456
	v_bfe_u32 v2, v4, 16, 1
	v_add3_u32 v2, v4, v2, s77
	v_add_f32_e32 v1, v4, v1
	ds_write_b16_d16_hi v32, v2 offset:17488
	v_bfe_u32 v2, v0, 16, 1
	v_add_f32_e32 v1, v0, v1
	v_add3_u32 v0, v0, v2, s77
	ds_write_b16_d16_hi v32, v0 offset:17520
	s_nop 0
	v_add_f32_dpp v0, v1, v1 quad_perm:[1,0,3,2] row_mask:0xf bank_mask:0xf bound_ctrl:1
	s_nop 1
	v_add_f32_dpp v0, v0, v0 quad_perm:[2,3,0,1] row_mask:0xf bank_mask:0xf bound_ctrl:1
	s_nop 1
	v_add_f32_dpp v0, v0, v0 row_half_mirror row_mask:0xf bank_mask:0xf bound_ctrl:1
	s_nop 1
	v_mov_b32_dpp v1, v0 row_ror:8 row_mask:0xf bank_mask:0xf bound_ctrl:1
	s_and_saveexec_b64 s[4:5], vcc
	v_add_f32_e32 v0, v0, v1
	ds_write_b32 v48, v0 offset:204
	s_or_b64 exec, exec, s[4:5]
	s_lshl_b32 s4, s42, 10
	s_or_b32 s4, s4, s41
	v_add_u32_e32 v0, s4, v65
	v_add_u32_e32 v8, s4, v67
	v_add_u32_e32 v16, s4, v69
	v_add_u32_e32 v26, s4, v71
	v_ashrrev_i32_e32 v1, 31, v0
	v_ashrrev_i32_e32 v9, 31, v8
	v_ashrrev_i32_e32 v17, 31, v16
	v_ashrrev_i32_e32 v27, 31, v26
	v_lshl_add_u64 v[24:25], s[28:29], 0, v[100:101]
	v_lshlrev_b64 v[0:1], 9, v[0:1]
	v_lshlrev_b64 v[8:9], 9, v[8:9]
	v_lshlrev_b64 v[16:17], 9, v[16:17]
	v_lshlrev_b64 v[26:27], 9, v[26:27]
	v_lshl_add_u64 v[28:29], v[24:25], 0, v[0:1]
	v_add_u32_e32 v0, s4, v66
	v_lshl_add_u64 v[32:33], v[24:25], 0, v[8:9]
	v_add_u32_e32 v8, s4, v68
	v_lshl_add_u64 v[36:37], v[24:25], 0, v[16:17]
	v_add_u32_e32 v16, s4, v70
	v_lshl_add_u64 v[68:69], v[24:25], 0, v[26:27]
	v_add_u32_e32 v26, s4, v72
	v_ashrrev_i32_e32 v1, 31, v0
	v_ashrrev_i32_e32 v9, 31, v8
	v_ashrrev_i32_e32 v17, 31, v16
	v_ashrrev_i32_e32 v27, 31, v26
	v_lshlrev_b64 v[0:1], 9, v[0:1]
	v_lshlrev_b64 v[8:9], 9, v[8:9]
	v_lshlrev_b64 v[16:17], 9, v[16:17]
	v_lshlrev_b64 v[26:27], 9, v[26:27]
	v_lshl_add_u64 v[30:31], v[24:25], 0, v[0:1]
	global_load_dwordx4 v[0:3], v[28:29], off
	global_load_dwordx4 v[4:7], v[30:31], off
	v_lshl_add_u64 v[34:35], v[24:25], 0, v[8:9]
	global_load_dwordx4 v[8:11], v[32:33], off
	global_load_dwordx4 v[12:15], v[34:35], off
	v_lshl_add_u64 v[38:39], v[24:25], 0, v[16:17]
	global_load_dwordx4 v[16:19], v[36:37], off
	global_load_dwordx4 v[20:23], v[38:39], off
	v_lshl_add_u64 v[70:71], v[24:25], 0, v[26:27]
	global_load_dwordx4 v[24:27], v[68:69], off
	global_load_dwordx4 v[40:43], v[70:71], off
	s_waitcnt lgkmcnt(0)
	s_barrier
; #define MFMA(a, b, c) __builtin_amdgcn_mfma_f32_16x16x32_bf16((a), (b), (c), 0, 0, 0)
; __device__ __forceinline__ void xattn_item(const Params& p, char* smem, const int tile, const int hm) {
;     ...
;     for (int kt = 0; kt < 4; ++kt) {
; #pragma unroll
;       for (int i = 0; i < 8; ++i) {
;         const int c = tid + 256 * i, row = c >> 3, cc = c & 7;
;         st[i] = *(const u32x4*)(vtm + (size_t)(b * 1024 + hm * 256 + row) * 256 + kt * 64 + cc * 8);
;       }
;       __syncthreads();
; #pragma unroll
;       for (int i = 0; i < 8; ++i) {
;         const int c = tid + 256 * i, row = c >> 3, cc = c & 7;
;         *(u32x4*)(sT + row * 72 + cc * 8) = st[i];
;       }
;       __syncthreads();
; #pragma unroll
;       for (int ks = 0; ks < 2; ++ks) {
;         bf16x8 pf[4], vf[4];
; #pragma unroll
;         for (int m = 0; m < 4; ++m) pf[m] = *(const bf16x8*)(sQ + (m * 16 + l15) * 264 + kt * 64 + ks * 32 + lq * 8);
; #pragma unroll
;         for (int n = 0; n < 4; ++n) vf[n] = *(const bf16x8*)(sT + (w * 64 + n * 16 + l15) * 72 + ks * 32 + lq * 8);
; #pragma unroll
;         for (int m = 0; m < 4; ++m)
; #pragma unroll
;           for (int n = 0; n < 4; ++n) acc[m][n] = MFMA(vf[n], pf[m], acc[m][n]);
;       }
	s_add_u32 s4, s14, s40
	v_or_b32_e32 v126, 16, v112
	v_ashrrev_i32_e32 v97, 31, v96
	v_lshlrev_b32_e32 v100, 1, v113
	v_lshlrev_b32_e32 v113, 2, v112
	s_addc_u32 s5, s15, 0
	v_or_b32_e32 v127, 0x11800, v113
	v_or_b32_e32 v128, 0x11900, v113
	v_or_b32_e32 v129, 0x11a00, v113
	v_lshlrev_b32_e32 v117, 2, v126
	v_or_b32_e32 v208, 0x11b00, v113
	v_or_b32_e32 v115, 32, v112
	v_or_b32_e32 v114, 48, v112
	s_waitcnt vmcnt(7)
	ds_write_b128 v98, v[0:3] offset:33792
	s_waitcnt vmcnt(6)
	ds_write_b128 v99, v[4:7] offset:33792
	s_waitcnt vmcnt(5)
	ds_write_b128 v104, v[8:11] offset:33792
	s_waitcnt vmcnt(4)
	ds_write_b128 v105, v[12:15] offset:33792
	s_waitcnt vmcnt(3)
	ds_write_b128 v106, v[16:19] offset:33792
	s_waitcnt vmcnt(2)
	ds_write_b128 v108, v[20:23] offset:33792
	s_waitcnt vmcnt(1)
	ds_write_b128 v109, v[24:27] offset:33792
	s_waitcnt vmcnt(0)
	ds_write_b128 v110, v[40:43] offset:33792
	s_waitcnt lgkmcnt(0)
	s_barrier
	ds_read_b128 v[0:3], v107 offset:33792
	v_mul_u32_u24_e32 v4, 0x210, v112
	v_add_u32_e32 v116, v64, v4
	ds_read_b128 v[4:7], v116
	ds_read_b128 v[8:11], v116 offset:64
	ds_read_b128 v[12:15], v107 offset:33856
	ds_read_b128 v[20:23], v107 offset:36096
	ds_read_b128 v[24:27], v107 offset:36160
	ds_read_b128 v[44:47], v107 offset:38400
	ds_read_b128 v[48:51], v107 offset:38464
	ds_read_b128 v[56:59], v111 offset:33792
	ds_read_b128 v[60:63], v111 offset:33856
	ds_read_b128 v[64:67], v116 offset:8448
	ds_read_b128 v[72:75], v116 offset:8512
	ds_read_b128 v[88:91], v116 offset:16896
	ds_read_b128 v[92:95], v116 offset:16960
	ds_read_b128 v[152:155], v116 offset:25344
	ds_read_b128 v[156:159], v116 offset:25408
	s_waitcnt lgkmcnt(14)
	v_mfma_f32_16x16x32_bf16 v[16:19], v[0:3], v[4:7], 0
	v_or_b32_e32 v112, s6, v112
	v_ashrrev_i32_e32 v113, 31, v112
	v_lshlrev_b64 v[112:113], 11, v[112:113]
	s_waitcnt lgkmcnt(11)
	v_mfma_f32_16x16x32_bf16 v[40:43], v[20:23], v[4:7], 0
	s_waitcnt lgkmcnt(9)
	v_mfma_f32_16x16x32_bf16 v[52:55], v[44:47], v[4:7], 0
	s_waitcnt lgkmcnt(7)
	v_mfma_f32_16x16x32_bf16 v[4:7], v[56:59], v[4:7], 0
	s_waitcnt lgkmcnt(5)
	v_mfma_f32_16x16x32_bf16 v[76:79], v[0:3], v[64:67], 0
	v_mfma_f32_16x16x32_bf16 v[80:83], v[20:23], v[64:67], 0
	v_mfma_f32_16x16x32_bf16 v[84:87], v[44:47], v[64:67], 0
	v_mfma_f32_16x16x32_bf16 v[64:67], v[56:59], v[64:67], 0
	s_waitcnt lgkmcnt(3)
	v_mfma_f32_16x16x32_bf16 v[140:143], v[0:3], v[88:91], 0
	v_mfma_f32_16x16x32_bf16 v[144:147], v[20:23], v[88:91], 0
	v_mfma_f32_16x16x32_bf16 v[148:151], v[44:47], v[88:91], 0
	v_mfma_f32_16x16x32_bf16 v[88:91], v[56:59], v[88:91], 0
	s_waitcnt lgkmcnt(1)
	v_mfma_f32_16x16x32_bf16 v[0:3], v[0:3], v[152:155], 0
	v_mfma_f32_16x16x32_bf16 v[20:23], v[20:23], v[152:155], 0
	v_mfma_f32_16x16x32_bf16 v[44:47], v[44:47], v[152:155], 0
	v_mfma_f32_16x16x32_bf16 v[56:59], v[56:59], v[152:155], 0
	v_mfma_f32_16x16x32_bf16 v[16:19], v[12:15], v[8:11], v[16:19]
	v_mfma_f32_16x16x32_bf16 v[40:43], v[24:27], v[8:11], v[40:43]
	v_mfma_f32_16x16x32_bf16 v[52:55], v[48:51], v[8:11], v[52:55]
	v_mfma_f32_16x16x32_bf16 v[4:7], v[60:63], v[8:11], v[4:7]
	v_mfma_f32_16x16x32_bf16 v[8:11], v[12:15], v[72:75], v[76:79]
	v_mfma_f32_16x16x32_bf16 v[76:79], v[24:27], v[72:75], v[80:83]
	v_mfma_f32_16x16x32_bf16 v[80:83], v[48:51], v[72:75], v[84:87]
	v_mfma_f32_16x16x32_bf16 v[64:67], v[60:63], v[72:75], v[64:67]
	v_mfma_f32_16x16x32_bf16 v[72:75], v[12:15], v[92:95], v[140:143]
	v_mfma_f32_16x16x32_bf16 v[84:87], v[24:27], v[92:95], v[144:147]
	v_mfma_f32_16x16x32_bf16 v[140:143], v[48:51], v[92:95], v[148:151]
	s_nop 1
	global_load_dwordx4 v[144:147], v[28:29], off offset:128
	global_load_dwordx4 v[148:151], v[30:31], off offset:128
	v_mfma_f32_16x16x32_bf16 v[88:91], v[60:63], v[92:95], v[88:91]
	global_load_dwordx4 v[92:95], v[32:33], off offset:128
	global_load_dwordx4 v[152:155], v[34:35], off offset:128
	global_load_dwordx4 v[160:163], v[36:37], off offset:128
	global_load_dwordx4 v[164:167], v[38:39], off offset:128
	s_waitcnt lgkmcnt(0)
	v_mfma_f32_16x16x32_bf16 v[0:3], v[12:15], v[156:159], v[0:3]
	global_load_dwordx4 v[12:15], v[68:69], off offset:128
	global_load_dwordx4 v[168:171], v[70:71], off offset:128
	s_barrier
	s_waitcnt vmcnt(7)
	ds_write_b128 v98, v[144:147] offset:33792
	s_waitcnt vmcnt(6)
	ds_write_b128 v99, v[148:151] offset:33792
	s_waitcnt vmcnt(5)
	ds_write_b128 v104, v[92:95] offset:33792
	s_waitcnt vmcnt(4)
	ds_write_b128 v105, v[152:155] offset:33792
	s_waitcnt vmcnt(3)
	ds_write_b128 v106, v[160:163] offset:33792
	s_waitcnt vmcnt(2)
	ds_write_b128 v108, v[164:167] offset:33792
	s_waitcnt vmcnt(1)
	ds_write_b128 v109, v[12:15] offset:33792
	s_waitcnt vmcnt(0)
	ds_write_b128 v110, v[168:171] offset:33792
	s_waitcnt lgkmcnt(0)
	s_barrier
; #define MFMA(a, b, c) __builtin_amdgcn_mfma_f32_16x16x32_bf16((a), (b), (c), 0, 0, 0)
; __device__ __forceinline__ void xattn_item(const Params& p, char* smem, const int tile, const int hm) {
;     ...
;     for (int kt = 0; kt < 4; ++kt) {
; #pragma unroll
;       for (int i = 0; i < 8; ++i) {
;         const int c = tid + 256 * i, row = c >> 3, cc = c & 7;
;         st[i] = *(const u32x4*)(vtm + (size_t)(b * 1024 + hm * 256 + row) * 256 + kt * 64 + cc * 8);
;       }
;       __syncthreads();
; #pragma unroll
;       for (int i = 0; i < 8; ++i) {
;         const int c = tid + 256 * i, row = c >> 3, cc = c & 7;
;         *(u32x4*)(sT + row * 72 + cc * 8) = st[i];
;       }
;       __syncthreads();
; #pragma unroll
;       for (int ks = 0; ks < 2; ++ks) {
;         bf16x8 pf[4], vf[4];
; #pragma unroll
;         for (int m = 0; m < 4; ++m) pf[m] = *(const bf16x8*)(sQ + (m * 16 + l15) * 264 + kt * 64 + ks * 32 + lq * 8);
; #pragma unroll
;         for (int n = 0; n < 4; ++n) vf[n] = *(const bf16x8*)(sT + (w * 64 + n * 16 + l15) * 72 + ks * 32 + lq * 8);
; #pragma unroll
;         for (int m = 0; m < 4; ++m)
; #pragma unroll
;           for (int n = 0; n < 4; ++n) acc[m][n] = MFMA(vf[n], pf[m], acc[m][n]);
;       }
	ds_read_b128 v[12:15], v107 offset:33792
	v_mfma_f32_16x16x32_bf16 v[20:23], v[24:27], v[156:159], v[20:23]
	v_mfma_f32_16x16x32_bf16 v[24:27], v[48:51], v[156:159], v[44:47]
	v_mfma_f32_16x16x32_bf16 v[44:47], v[60:63], v[156:159], v[56:59]
	ds_read_b128 v[48:51], v116 offset:128
	s_nop 1
	ds_read_b128 v[56:59], v116 offset:192
	ds_read_b128 v[60:63], v107 offset:33856
	ds_read_b128 v[92:95], v107 offset:36096
	ds_read_b128 v[144:147], v107 offset:36160
	ds_read_b128 v[148:151], v107 offset:38400
	ds_read_b128 v[152:155], v107 offset:38464
	ds_read_b128 v[156:159], v111 offset:33792
	ds_read_b128 v[160:163], v111 offset:33856
	s_waitcnt lgkmcnt(8)
	v_mfma_f32_16x16x32_bf16 v[16:19], v[12:15], v[48:51], v[16:19]
	s_waitcnt lgkmcnt(5)
	v_mfma_f32_16x16x32_bf16 v[40:43], v[92:95], v[48:51], v[40:43]
	s_waitcnt lgkmcnt(3)
	v_mfma_f32_16x16x32_bf16 v[52:55], v[148:151], v[48:51], v[52:55]
	s_waitcnt lgkmcnt(1)
	v_mfma_f32_16x16x32_bf16 v[4:7], v[156:159], v[48:51], v[4:7]
	ds_read_b128 v[48:51], v116 offset:8576
	ds_read_b128 v[164:167], v116 offset:8640
	s_waitcnt lgkmcnt(1)
	v_mfma_f32_16x16x32_bf16 v[8:11], v[12:15], v[48:51], v[8:11]
	v_mfma_f32_16x16x32_bf16 v[76:79], v[92:95], v[48:51], v[76:79]
	v_mfma_f32_16x16x32_bf16 v[80:83], v[148:151], v[48:51], v[80:83]
	v_mfma_f32_16x16x32_bf16 v[48:51], v[156:159], v[48:51], v[64:67]
	s_nop 2
	ds_read_b128 v[64:67], v116 offset:17024
	ds_read_b128 v[168:171], v116 offset:17088
	s_waitcnt lgkmcnt(1)
	v_mfma_f32_16x16x32_bf16 v[72:75], v[12:15], v[64:67], v[72:75]
	v_mfma_f32_16x16x32_bf16 v[84:87], v[92:95], v[64:67], v[84:87]
	v_mfma_f32_16x16x32_bf16 v[140:143], v[148:151], v[64:67], v[140:143]
	v_mfma_f32_16x16x32_bf16 v[64:67], v[156:159], v[64:67], v[88:91]
	s_nop 2
	ds_read_b128 v[88:91], v116 offset:25472
	ds_read_b128 v[172:175], v116 offset:25536
	s_waitcnt lgkmcnt(1)
	v_mfma_f32_16x16x32_bf16 v[0:3], v[12:15], v[88:91], v[0:3]
	v_mfma_f32_16x16x32_bf16 v[12:15], v[92:95], v[88:91], v[20:23]
	v_mfma_f32_16x16x32_bf16 v[20:23], v[148:151], v[88:91], v[24:27]
	v_mfma_f32_16x16x32_bf16 v[24:27], v[156:159], v[88:91], v[44:47]
	v_mfma_f32_16x16x32_bf16 v[16:19], v[60:63], v[56:59], v[16:19]
	v_mfma_f32_16x16x32_bf16 v[40:43], v[144:147], v[56:59], v[40:43]
	v_mfma_f32_16x16x32_bf16 v[44:47], v[152:155], v[56:59], v[52:55]
	v_mfma_f32_16x16x32_bf16 v[148:151], v[160:163], v[56:59], v[4:7]
	v_mfma_f32_16x16x32_bf16 v[156:159], v[60:63], v[164:167], v[8:11]
	s_nop 1
	global_load_dwordx4 v[4:7], v[28:29], off offset:256
	global_load_dwordx4 v[8:11], v[30:31], off offset:256
	v_mfma_f32_16x16x32_bf16 v[176:179], v[144:147], v[164:167], v[76:79]
	v_mfma_f32_16x16x32_bf16 v[80:83], v[152:155], v[164:167], v[80:83]
	v_mfma_f32_16x16x32_bf16 v[164:167], v[160:163], v[164:167], v[48:51]
	v_mfma_f32_16x16x32_bf16 v[180:183], v[60:63], v[168:171], v[72:75]
	s_nop 1
	global_load_dwordx4 v[48:51], v[32:33], off offset:256
	global_load_dwordx4 v[56:59], v[34:35], off offset:256
	global_load_dwordx4 v[72:75], v[36:37], off offset:256
	global_load_dwordx4 v[76:79], v[38:39], off offset:256
	v_mfma_f32_16x16x32_bf16 v[184:187], v[144:147], v[168:171], v[84:87]
	s_nop 2
	global_load_dwordx4 v[84:87], v[68:69], off offset:256
	global_load_dwordx4 v[88:91], v[70:71], off offset:256
	s_waitcnt lgkmcnt(0)
	s_barrier
	s_waitcnt vmcnt(7)
	ds_write_b128 v98, v[4:7] offset:33792
	s_waitcnt vmcnt(6)
	ds_write_b128 v99, v[8:11] offset:33792
	s_waitcnt vmcnt(5)
	ds_write_b128 v104, v[48:51] offset:33792
	s_waitcnt vmcnt(4)
	ds_write_b128 v105, v[56:59] offset:33792
	s_waitcnt vmcnt(3)
	ds_write_b128 v106, v[72:75] offset:33792
	s_waitcnt vmcnt(2)
	ds_write_b128 v108, v[76:79] offset:33792
	s_waitcnt vmcnt(1)
	ds_write_b128 v109, v[84:87] offset:33792
	s_waitcnt vmcnt(0)
	ds_write_b128 v110, v[88:91] offset:33792
	s_waitcnt lgkmcnt(0)
	s_barrier
	ds_read_b128 v[72:75], v107 offset:33792
	v_mfma_f32_16x16x32_bf16 v[140:143], v[152:155], v[168:171], v[140:143]
	v_mfma_f32_16x16x32_bf16 v[168:171], v[160:163], v[168:171], v[64:67]
	v_mfma_f32_16x16x32_bf16 v[52:55], v[60:63], v[172:175], v[0:3]
	v_mfma_f32_16x16x32_bf16 v[64:67], v[144:147], v[172:175], v[12:15]
	v_mfma_f32_16x16x32_bf16 v[56:59], v[152:155], v[172:175], v[20:23]
	v_mfma_f32_16x16x32_bf16 v[60:63], v[160:163], v[172:175], v[24:27]
	s_nop 2
	ds_read_b128 v[24:27], v116 offset:256
	ds_read_b128 v[20:23], v116 offset:320
	ds_read_b128 v[12:15], v107 offset:33856
	ds_read_b128 v[92:95], v107 offset:36096
	ds_read_b128 v[8:11], v107 offset:36160
	ds_read_b128 v[88:91], v107 offset:38400
	ds_read_b128 v[0:3], v107 offset:38464
	ds_read_b128 v[84:87], v111 offset:33792
	ds_read_b128 v[144:147], v116 offset:8704
	ds_read_b128 v[4:7], v111 offset:33856
	s_waitcnt lgkmcnt(9)
	v_mfma_f32_16x16x32_bf16 v[76:79], v[72:75], v[24:27], v[16:19]
	s_waitcnt lgkmcnt(6)
	v_mfma_f32_16x16x32_bf16 v[48:51], v[92:95], v[24:27], v[40:43]
	s_nop 0
	ds_read_b128 v[16:19], v116 offset:8768
	s_waitcnt lgkmcnt(5)
	v_mfma_f32_16x16x32_bf16 v[40:43], v[88:91], v[24:27], v[44:47]
	s_waitcnt lgkmcnt(3)
	v_mfma_f32_16x16x32_bf16 v[24:27], v[84:87], v[24:27], v[148:151]
	s_nop 2
	global_load_dwordx4 v[148:151], v[28:29], off offset:384
	global_load_dwordx4 v[152:155], v[30:31], off offset:384
	s_waitcnt lgkmcnt(2)
	v_mfma_f32_16x16x32_bf16 v[44:47], v[72:75], v[144:147], v[156:159]
	s_nop 2
	global_load_dwordx4 v[156:159], v[32:33], off offset:384
	global_load_dwordx4 v[160:163], v[34:35], off offset:384
	global_load_dwordx4 v[172:175], v[36:37], off offset:384
	global_load_dwordx4 v[188:191], v[38:39], off offset:384
	v_mfma_f32_16x16x32_bf16 v[36:39], v[92:95], v[144:147], v[176:179]
	s_nop 2
	global_load_dwordx4 v[176:179], v[68:69], off offset:384
	global_load_dwordx4 v[198:201], v[70:71], off offset:384
	ds_read_b128 v[202:205], v116 offset:17152
	ds_read_b128 v[68:71], v116 offset:17216
	v_mfma_f32_16x16x32_bf16 v[32:35], v[84:87], v[144:147], v[164:167]
	s_nop 2
	ds_read_b128 v[164:167], v116 offset:25600
	v_mfma_f32_16x16x32_bf16 v[28:31], v[88:91], v[144:147], v[80:83]
	s_waitcnt lgkmcnt(2)
	v_mfma_f32_16x16x32_bf16 v[80:83], v[72:75], v[202:205], v[180:183]
	s_nop 2
	ds_read_b128 v[180:183], v116 offset:25664
	s_waitcnt lgkmcnt(1)
	v_mfma_f32_16x16x32_bf16 v[72:75], v[72:75], v[164:167], v[52:55]
	s_waitcnt lgkmcnt(0)
	s_barrier
; __device__ __forceinline__ unsigned pack2(float a, float b) { return (unsigned)f2bf(a) | ((unsigned)f2bf(b) << 16); }
; #define MFMA(a, b, c) __builtin_amdgcn_mfma_f32_16x16x32_bf16((a), (b), (c), 0, 0, 0)
; __device__ __forceinline__ void xattn_item(const Params& p, char* smem, const int tile, const int hm) {
;     ...
;     for (int kt = 0; kt < 4; ++kt) {
; #pragma unroll
;       for (int i = 0; i < 8; ++i) {
;         const int c = tid + 256 * i, row = c >> 3, cc = c & 7;
;         st[i] = *(const u32x4*)(vtm + (size_t)(b * 1024 + hm * 256 + row) * 256 + kt * 64 + cc * 8);
;       }
;       __syncthreads();
; #pragma unroll
;       for (int i = 0; i < 8; ++i) {
;         const int c = tid + 256 * i, row = c >> 3, cc = c & 7;
;         *(u32x4*)(sT + row * 72 + cc * 8) = st[i];
;       }
;       __syncthreads();
; #pragma unroll
;       for (int ks = 0; ks < 2; ++ks) {
;         bf16x8 pf[4], vf[4];
; #pragma unroll
;         for (int m = 0; m < 4; ++m) pf[m] = *(const bf16x8*)(sQ + (m * 16 + l15) * 264 + kt * 64 + ks * 32 + lq * 8);
; #pragma unroll
;         for (int n = 0; n < 4; ++n) vf[n] = *(const bf16x8*)(sT + (w * 64 + n * 16 + l15) * 72 + ks * 32 + lq * 8);
; #pragma unroll
;         for (int m = 0; m < 4; ++m)
; #pragma unroll
;           for (int n = 0; n < 4; ++n) acc[m][n] = MFMA(vf[n], pf[m], acc[m][n]);
;       }
;     }
; #pragma unroll
;     for (int m = 0; m < 4; ++m) {
;       const int row = m * 16 + l15;
;       const float inv = 1.f / (sSum[row] + sSum[64 + row] + sSum[128 + row] + sSum[192 + row]);
; #pragma unroll
;       for (int n = 0; n < 4; ++n)
;         *(uint2*)(xo + (size_t)(tok0 + row) * 1024 + hm * 256 + w * 64 + n * 16 + lq * 4) =
;             make_uint2(pack2(acc[m][n][0] * inv, acc[m][n][1] * inv), pack2(acc[m][n][2] * inv, acc[m][n][3] * inv));
;     }
	s_nop 0
	v_lshl_add_u64 v[52:53], v[96:97], 1, s[4:5]
	v_mfma_f32_16x16x32_bf16 v[144:147], v[92:95], v[202:205], v[184:187]
	v_lshl_add_u64 v[52:53], v[52:53], 0, v[100:101]
	s_waitcnt vmcnt(7)
	ds_write_b128 v98, v[148:151] offset:33792
	s_waitcnt vmcnt(6)
	ds_write_b128 v99, v[152:155] offset:33792
	s_waitcnt vmcnt(5)
	ds_write_b128 v104, v[156:159] offset:33792
	s_waitcnt vmcnt(4)
	ds_write_b128 v105, v[160:163] offset:33792
	s_waitcnt vmcnt(3)
	ds_write_b128 v106, v[172:175] offset:33792
	s_waitcnt vmcnt(2)
	ds_write_b128 v108, v[188:191] offset:33792
	s_waitcnt vmcnt(1)
	ds_write_b128 v109, v[176:179] offset:33792
	s_waitcnt vmcnt(0)
	ds_write_b128 v110, v[198:201] offset:33792
	v_mfma_f32_16x16x32_bf16 v[140:143], v[88:91], v[202:205], v[140:143]
	s_waitcnt lgkmcnt(0)
	s_barrier
	v_mfma_f32_16x16x32_bf16 v[168:171], v[84:87], v[202:205], v[168:171]
	v_or_b32_e32 v202, 0x11800, v117
	v_or_b32_e32 v203, 0x11900, v117
	v_or_b32_e32 v204, 0x11a00, v117
	v_mfma_f32_16x16x32_bf16 v[64:67], v[92:95], v[164:167], v[64:67]
	v_or_b32_e32 v205, 0x11b00, v117
	v_lshl_add_u64 v[112:113], v[52:53], 0, v[112:113]
	v_mfma_f32_16x16x32_bf16 v[54:57], v[88:91], v[164:167], v[56:59]
	v_mfma_f32_16x16x32_bf16 v[58:61], v[84:87], v[164:167], v[60:63]
	ds_read_b128 v[84:87], v116 offset:384
	ds_read_b128 v[88:91], v116 offset:448
	ds_read_b128 v[92:95], v116 offset:8832
	ds_read_b128 v[96:99], v116 offset:8896
	ds_read_b128 v[148:151], v116 offset:17280
	ds_read_b128 v[152:155], v116 offset:17344
	ds_read_b128 v[156:159], v116 offset:25728
	ds_read_b128 v[116:119], v116 offset:25792
	ds_read_b128 v[160:163], v107 offset:33792
	ds_read_b128 v[164:167], v107 offset:33856
	ds_read_b128 v[172:175], v107 offset:36096
	ds_read_b128 v[176:179], v107 offset:36160
	ds_read_b128 v[184:187], v107 offset:38400
	ds_read_b128 v[104:107], v107 offset:38464
	ds_read_b128 v[188:191], v111 offset:33792
	ds_read_b128 v[108:111], v111 offset:33856
	ds_read_b32 v62, v127
	ds_read_b32 v63, v128
	ds_read_b32 v100, v129
	ds_read_b32 v127, v208
	ds_read_b32 v128, v202
	ds_read_b32 v129, v203
	ds_read_b32 v198, v204
	ds_read_b32 v199, v205
	s_waitcnt lgkmcnt(6)
	v_add_f32_e32 v62, v62, v63
	v_mfma_f32_16x16x32_bf16 v[76:79], v[12:15], v[20:23], v[76:79]
	s_waitcnt lgkmcnt(5)
	v_add_f32_e32 v62, v62, v100
	s_waitcnt lgkmcnt(4)
	v_add_f32_e32 v100, v62, v127
	v_div_scale_f32 v127, s[4:5], v100, v100, 1.0
	v_mfma_f32_16x16x32_bf16 v[48:51], v[8:11], v[20:23], v[48:51]
	v_rcp_f32_e32 v200, v127
	v_div_scale_f32 v201, vcc, 1.0, v100, 1.0
	v_mfma_f32_16x16x32_bf16 v[76:79], v[160:163], v[84:87], v[76:79]
	v_fma_f32 v62, -v127, v200, 1.0
	v_fmac_f32_e32 v200, v62, v200
	v_mul_f32_e32 v202, v201, v200
	v_mfma_f32_16x16x32_bf16 v[48:51], v[172:175], v[84:87], v[48:51]
	v_fma_f32 v62, -v127, v202, v201
	v_fmac_f32_e32 v202, v62, v200
	v_mfma_f32_16x16x32_bf16 v[76:79], v[164:167], v[88:91], v[76:79]
	v_mfma_f32_16x16x32_bf16 v[48:51], v[176:179], v[88:91], v[48:51]
	v_mfma_f32_16x16x32_bf16 v[40:43], v[0:3], v[20:23], v[40:43]
	s_nop 5
	v_mov_b32_e32 v62, v76
	v_mov_b32_e32 v76, v48
	v_fma_f32 v48, -v127, v202, v201
	v_div_fmas_f32 v48, v48, v200, v202
	v_mov_b32_e32 v63, v78
	v_mov_b32_e32 v78, v77
	v_div_fixup_f32 v48, v48, v100, 1.0
	v_mov_b32_e32 v77, v50
	v_mov_b32_e32 v50, v49
	v_pk_mul_f32 v[62:63], v[62:63], v[48:49] op_sel_hi:[1,0]
	v_pk_mul_f32 v[78:79], v[78:79], v[48:49] op_sel_hi:[1,0]
	v_pk_mul_f32 v[76:77], v[76:77], v[48:49] op_sel_hi:[1,0]
	v_pk_mul_f32 v[50:51], v[50:51], v[48:49] op_sel_hi:[1,0]
	v_and_b32_sdwa v49, v63, v120 dst_sel:DWORD dst_unused:UNUSED_PAD src0_sel:WORD_1 src1_sel:DWORD
	v_and_b32_sdwa v127, v79, v120 dst_sel:DWORD dst_unused:UNUSED_PAD src0_sel:WORD_1 src1_sel:DWORD
	v_and_b32_sdwa v200, v78, v120 dst_sel:DWORD dst_unused:UNUSED_PAD src0_sel:WORD_1 src1_sel:DWORD
	v_mfma_f32_16x16x32_bf16 v[20:23], v[4:7], v[20:23], v[24:27]
	v_and_b32_sdwa v100, v62, v120 dst_sel:DWORD dst_unused:UNUSED_PAD src0_sel:WORD_1 src1_sel:DWORD
	v_add3_u32 v49, v63, v49, s77
	v_add3_u32 v63, v79, v127, s77
	v_mfma_f32_16x16x32_bf16 v[40:43], v[184:187], v[84:87], v[40:43]
	v_add3_u32 v78, v78, v200, s77
	v_add3_u32 v62, v62, v100, s77
	v_and_b32_e32 v63, 0xffff0000, v63
	v_and_b32_e32 v78, 0xffff0000, v78
	v_or_b32_sdwa v25, v63, v49 dst_sel:DWORD dst_unused:UNUSED_PAD src0_sel:DWORD src1_sel:WORD_1
	v_or_b32_sdwa v24, v78, v62 dst_sel:DWORD dst_unused:UNUSED_PAD src0_sel:DWORD src1_sel:WORD_1
	v_and_b32_sdwa v203, v51, v120 dst_sel:DWORD dst_unused:UNUSED_PAD src0_sel:WORD_1 src1_sel:DWORD
	global_store_dwordx2 v[112:113], v[24:25], off
	v_mfma_f32_16x16x32_bf16 v[24:27], v[12:15], v[16:19], v[44:47]
	v_and_b32_sdwa v201, v77, v120 dst_sel:DWORD dst_unused:UNUSED_PAD src0_sel:WORD_1 src1_sel:DWORD
	v_and_b32_sdwa v202, v76, v120 dst_sel:DWORD dst_unused:UNUSED_PAD src0_sel:WORD_1 src1_sel:DWORD
	v_add3_u32 v76, v76, v202, s77
	v_and_b32_sdwa v44, v50, v120 dst_sel:DWORD dst_unused:UNUSED_PAD src0_sel:WORD_1 src1_sel:DWORD
	v_mfma_f32_16x16x32_bf16 v[40:43], v[104:107], v[88:91], v[40:43]
	v_add3_u32 v45, v51, v203, s77
	v_add3_u32 v44, v50, v44, s77
	v_add3_u32 v77, v77, v201, s77
	v_mfma_f32_16x16x32_bf16 v[20:23], v[188:191], v[84:87], v[20:23]
	v_and_b32_e32 v45, 0xffff0000, v45
	v_and_b32_e32 v44, 0xffff0000, v44
	v_or_b32_sdwa v45, v45, v77 dst_sel:DWORD dst_unused:UNUSED_PAD src0_sel:DWORD src1_sel:WORD_1
	v_or_b32_sdwa v44, v44, v76 dst_sel:DWORD dst_unused:UNUSED_PAD src0_sel:DWORD src1_sel:WORD_1
	global_store_dwordx2 v[112:113], v[44:45], off offset:32
	v_mov_b32_e32 v44, v40
	v_mov_b32_e32 v45, v42
	v_mfma_f32_16x16x32_bf16 v[20:23], v[108:111], v[88:91], v[20:23]
; __device__ __forceinline__ unsigned pack2(float a, float b) { return (unsigned)f2bf(a) | ((unsigned)f2bf(b) << 16); }
; #define MFMA(a, b, c) __builtin_amdgcn_mfma_f32_16x16x32_bf16((a), (b), (c), 0, 0, 0)
; __device__ __forceinline__ void xattn_item(const Params& p, char* smem, const int tile, const int hm) {
;     ...
;         for (int m = 0; m < 4; ++m)
; #pragma unroll
;           for (int n = 0; n < 4; ++n) acc[m][n] = MFMA(vf[n], pf[m], acc[m][n]);
;       }
;     }
; #pragma unroll
;     for (int m = 0; m < 4; ++m) {
;       const int row = m * 16 + l15;
;       const float inv = 1.f / (sSum[row] + sSum[64 + row] + sSum[128 + row] + sSum[192 + row]);
; #pragma unroll
;       for (int n = 0; n < 4; ++n)
;         *(uint2*)(xo + (size_t)(tok0 + row) * 1024 + hm * 256 + w * 64 + n * 16 + lq * 4) =
;             make_uint2(pack2(acc[m][n][0] * inv, acc[m][n][1] * inv), pack2(acc[m][n][2] * inv, acc[m][n][3] * inv));
;     }
	v_mul_f32_e64 v44, v44, v48
	v_mul_f32_e64 v45, v45, v48
	v_mov_b32_e32 v42, v41
	v_pk_mul_f32 v[40:41], v[42:43], v[48:49] op_sel_hi:[1,0]
	v_and_b32_sdwa v42, v45, v120 dst_sel:DWORD dst_unused:UNUSED_PAD src0_sel:WORD_1 src1_sel:DWORD
	v_and_b32_sdwa v43, v44, v120 dst_sel:DWORD dst_unused:UNUSED_PAD src0_sel:WORD_1 src1_sel:DWORD
	v_add3_u32 v43, v44, v43, s77
	v_add3_u32 v42, v45, v42, s77
	v_and_b32_sdwa v44, v41, v120 dst_sel:DWORD dst_unused:UNUSED_PAD src0_sel:WORD_1 src1_sel:DWORD
	v_and_b32_sdwa v45, v40, v120 dst_sel:DWORD dst_unused:UNUSED_PAD src0_sel:WORD_1 src1_sel:DWORD
	v_add3_u32 v41, v41, v44, s77
	v_add3_u32 v40, v40, v45, s77
	v_mov_b32_e32 v44, v20
	v_mov_b32_e32 v45, v22
	v_pk_mul_f32 v[62:63], v[44:45], v[48:49] op_sel_hi:[1,0]
	v_mov_b32_e32 v22, v21
	v_pk_mul_f32 v[20:21], v[22:23], v[48:49] op_sel_hi:[1,0]
	v_and_b32_sdwa v23, v62, v120 dst_sel:DWORD dst_unused:UNUSED_PAD src0_sel:WORD_1 src1_sel:DWORD
	v_add3_u32 v23, v62, v23, s77
	v_and_b32_sdwa v62, v21, v120 dst_sel:DWORD dst_unused:UNUSED_PAD src0_sel:WORD_1 src1_sel:DWORD
	v_and_b32_sdwa v22, v63, v120 dst_sel:DWORD dst_unused:UNUSED_PAD src0_sel:WORD_1 src1_sel:DWORD
	v_add3_u32 v21, v21, v62, s77
	v_add3_u32 v22, v63, v22, s77
	v_and_b32_sdwa v63, v20, v120 dst_sel:DWORD dst_unused:UNUSED_PAD src0_sel:WORD_1 src1_sel:DWORD
	v_and_b32_e32 v21, 0xffff0000, v21
	v_add3_u32 v20, v20, v63, s77
	v_or_b32_sdwa v63, v21, v22 dst_sel:DWORD dst_unused:UNUSED_PAD src0_sel:DWORD src1_sel:WORD_1
	s_waitcnt lgkmcnt(2)
	v_add_f32_e32 v21, v128, v129
	s_waitcnt lgkmcnt(1)
	v_add_f32_e32 v21, v21, v198
	v_mfma_f32_16x16x32_bf16 v[28:31], v[0:3], v[16:19], v[28:31]
	v_and_b32_e32 v20, 0xffff0000, v20
	v_or_b32_sdwa v62, v20, v23 dst_sel:DWORD dst_unused:UNUSED_PAD src0_sel:DWORD src1_sel:WORD_1
	v_and_b32_e32 v41, 0xffff0000, v41
	v_mfma_f32_16x16x32_bf16 v[44:47], v[0:3], v[68:71], v[140:143]
	v_and_b32_e32 v40, 0xffff0000, v40
	v_or_b32_sdwa v41, v41, v42 dst_sel:DWORD dst_unused:UNUSED_PAD src0_sel:DWORD src1_sel:WORD_1
	v_or_b32_sdwa v40, v40, v43 dst_sel:DWORD dst_unused:UNUSED_PAD src0_sel:DWORD src1_sel:WORD_1
	v_mfma_f32_16x16x32_bf16 v[0:3], v[0:3], v[180:183], v[54:57]
	global_store_dwordx2 v[112:113], v[40:41], off offset:64
	global_store_dwordx2 v[112:113], v[62:63], off offset:96
	s_waitcnt lgkmcnt(0)
	v_add_f32_e32 v54, v21, v199
	v_div_scale_f32 v55, s[4:5], v54, v54, 1.0
	v_rcp_f32_e32 v56, v55
	v_mfma_f32_16x16x32_bf16 v[36:39], v[8:11], v[16:19], v[36:39]
	v_mfma_f32_16x16x32_bf16 v[20:23], v[160:163], v[92:95], v[24:27]
	s_nop 2
	v_fma_f32 v24, -v55, v56, 1.0
	v_fmac_f32_e32 v56, v24, v56
	v_mfma_f32_16x16x32_bf16 v[24:27], v[172:175], v[92:95], v[36:39]
	s_nop 2
	v_div_scale_f32 v36, vcc, 1.0, v54, 1.0
	v_mul_f32_e32 v37, v36, v56
	v_fma_f32 v38, -v55, v37, v36
	v_fmac_f32_e32 v37, v38, v56
	v_fma_f32 v36, -v55, v37, v36
	v_div_fmas_f32 v36, v36, v56, v37
	v_div_fixup_f32 v54, v36, v54, 1.0
	v_or_b32_e32 v36, s6, v126
	v_ashrrev_i32_e32 v37, 31, v36
	v_lshlrev_b64 v[56:57], 11, v[36:37]
	v_mfma_f32_16x16x32_bf16 v[36:39], v[164:167], v[96:99], v[20:23]
	v_mfma_f32_16x16x32_bf16 v[48:51], v[4:7], v[68:71], v[168:171]
	s_nop 1
	v_lshl_add_u64 v[20:21], v[52:53], 0, v[56:57]
	s_nop 3
	v_mov_b32_e32 v22, v36
	v_mov_b32_e32 v23, v38
	v_pk_mul_f32 v[22:23], v[22:23], v[54:55] op_sel_hi:[1,0]
	v_mov_b32_e32 v38, v37
	v_pk_mul_f32 v[56:57], v[38:39], v[54:55] op_sel_hi:[1,0]
	v_mfma_f32_16x16x32_bf16 v[36:39], v[184:187], v[148:151], v[44:47]
	v_and_b32_sdwa v55, v23, v120 dst_sel:DWORD dst_unused:UNUSED_PAD src0_sel:WORD_1 src1_sel:DWORD
	v_add3_u32 v23, v23, v55, s77
	s_nop 0
	v_and_b32_sdwa v44, v22, v120 dst_sel:DWORD dst_unused:UNUSED_PAD src0_sel:WORD_1 src1_sel:DWORD
	v_add3_u32 v22, v22, v44, s77
	v_mfma_f32_16x16x32_bf16 v[44:47], v[188:191], v[148:151], v[48:51]
	s_nop 2
	v_and_b32_sdwa v48, v57, v120 dst_sel:DWORD dst_unused:UNUSED_PAD src0_sel:WORD_1 src1_sel:DWORD
	v_and_b32_sdwa v49, v56, v120 dst_sel:DWORD dst_unused:UNUSED_PAD src0_sel:WORD_1 src1_sel:DWORD
	v_add3_u32 v48, v57, v48, s77
	v_add3_u32 v49, v56, v49, s77
	v_and_b32_e32 v48, 0xffff0000, v48
	v_and_b32_e32 v50, 0xffff0000, v49
	v_mfma_f32_16x16x32_bf16 v[16:19], v[4:7], v[16:19], v[32:35]
	v_or_b32_sdwa v49, v48, v23 dst_sel:DWORD dst_unused:UNUSED_PAD src0_sel:DWORD src1_sel:WORD_1
	v_or_b32_sdwa v48, v50, v22 dst_sel:DWORD dst_unused:UNUSED_PAD src0_sel:DWORD src1_sel:WORD_1
	global_store_dwordx2 v[20:21], v[48:49], off
	v_mfma_f32_16x16x32_bf16 v[22:25], v[176:179], v[96:99], v[24:27]
	v_mfma_f32_16x16x32_bf16 v[4:7], v[4:7], v[180:183], v[58:61]
	v_mfma_f32_16x16x32_bf16 v[28:31], v[184:187], v[92:95], v[28:31]
	s_nop 5
	v_mov_b32_e32 v26, v22
	v_mov_b32_e32 v27, v24
	v_pk_mul_f32 v[26:27], v[26:27], v[54:55] op_sel_hi:[1,0]
	v_mfma_f32_16x16x32_bf16 v[32:35], v[12:15], v[68:71], v[80:83]
	v_mov_b32_e32 v24, v23
	v_pk_mul_f32 v[48:49], v[24:25], v[54:55] op_sel_hi:[1,0]
	v_and_b32_sdwa v50, v27, v120 dst_sel:DWORD dst_unused:UNUSED_PAD src0_sel:WORD_1 src1_sel:DWORD
	v_mfma_f32_16x16x32_bf16 v[16:19], v[188:191], v[92:95], v[16:19]
	v_add3_u32 v50, v27, v50, s77
	v_mfma_f32_16x16x32_bf16 v[22:25], v[188:191], v[156:159], v[4:7]
	s_nop 2
	v_and_b32_sdwa v4, v26, v120 dst_sel:DWORD dst_unused:UNUSED_PAD src0_sel:WORD_1 src1_sel:DWORD
	v_add3_u32 v51, v26, v4, s77
	v_mfma_f32_16x16x32_bf16 v[4:7], v[104:107], v[96:99], v[28:31]
	s_nop 2
	v_and_b32_sdwa v30, v49, v120 dst_sel:DWORD dst_unused:UNUSED_PAD src0_sel:WORD_1 src1_sel:DWORD
	v_and_b32_sdwa v31, v48, v120 dst_sel:DWORD dst_unused:UNUSED_PAD src0_sel:WORD_1 src1_sel:DWORD
	v_mfma_f32_16x16x32_bf16 v[32:35], v[160:163], v[148:151], v[32:35]
; __device__ __forceinline__ unsigned pack2(float a, float b) { return (unsigned)f2bf(a) | ((unsigned)f2bf(b) << 16); }
; #define MFMA(a, b, c) __builtin_amdgcn_mfma_f32_16x16x32_bf16((a), (b), (c), 0, 0, 0)
; __device__ __forceinline__ void xattn_item(const Params& p, char* smem, const int tile, const int hm) {
;     ...
;         for (int m = 0; m < 4; ++m)
; #pragma unroll
;           for (int n = 0; n < 4; ++n) acc[m][n] = MFMA(vf[n], pf[m], acc[m][n]);
;       }
;     }
; #pragma unroll
;     for (int m = 0; m < 4; ++m) {
;       const int row = m * 16 + l15;
;       const float inv = 1.f / (sSum[row] + sSum[64 + row] + sSum[128 + row] + sSum[192 + row]);
; #pragma unroll
;       for (int n = 0; n < 4; ++n)
;         *(uint2*)(xo + (size_t)(tok0 + row) * 1024 + hm * 256 + w * 64 + n * 16 + lq * 4) =
;             make_uint2(pack2(acc[m][n][0] * inv, acc[m][n][1] * inv), pack2(acc[m][n][2] * inv, acc[m][n][3] * inv));
;     }
	v_mfma_f32_16x16x32_bf16 v[26:29], v[108:111], v[96:99], v[16:19]
	s_nop 2
	v_add3_u32 v16, v49, v30, s77
	v_add3_u32 v17, v48, v31, s77
	v_and_b32_e32 v16, 0xffff0000, v16
	v_and_b32_e32 v18, 0xffff0000, v17
	v_or_b32_sdwa v17, v16, v50 dst_sel:DWORD dst_unused:UNUSED_PAD src0_sel:DWORD src1_sel:WORD_1
	v_or_b32_sdwa v16, v18, v51 dst_sel:DWORD dst_unused:UNUSED_PAD src0_sel:DWORD src1_sel:WORD_1
	global_store_dwordx2 v[20:21], v[16:17], off offset:32
	v_mov_b32_e32 v16, v4
	v_mov_b32_e32 v17, v6
	v_mfma_f32_16x16x32_bf16 v[0:3], v[184:187], v[156:159], v[0:3]
	v_mov_b32_e32 v6, v5
	v_pk_mul_f32 v[4:5], v[6:7], v[54:55] op_sel_hi:[1,0]
	v_mfma_f32_16x16x32_bf16 v[30:33], v[164:167], v[152:155], v[32:35]
	v_mfma_f32_16x16x32_bf16 v[34:37], v[104:107], v[152:155], v[36:39]
	s_nop 2
	v_mul_f32_e64 v38, v16, v54
	v_mul_f32_e64 v39, v17, v54
	v_mfma_f32_16x16x32_bf16 v[16:19], v[108:111], v[152:155], v[44:47]
	v_and_b32_sdwa v6, v39, v120 dst_sel:DWORD dst_unused:UNUSED_PAD src0_sel:WORD_1 src1_sel:DWORD
	v_and_b32_sdwa v7, v38, v120 dst_sel:DWORD dst_unused:UNUSED_PAD src0_sel:WORD_1 src1_sel:DWORD
	v_add3_u32 v38, v38, v7, s77
	v_add3_u32 v39, v39, v6, s77
	v_and_b32_sdwa v6, v5, v120 dst_sel:DWORD dst_unused:UNUSED_PAD src0_sel:WORD_1 src1_sel:DWORD
	v_and_b32_sdwa v7, v4, v120 dst_sel:DWORD dst_unused:UNUSED_PAD src0_sel:WORD_1 src1_sel:DWORD
	v_add3_u32 v5, v5, v6, s77
	v_add3_u32 v44, v4, v7, s77
	v_and_b32_e32 v45, 0xffff0000, v5
	v_mfma_f32_16x16x32_bf16 v[4:7], v[104:107], v[116:119], v[0:3]
	v_or_b32_sdwa v39, v45, v39 dst_sel:DWORD dst_unused:UNUSED_PAD src0_sel:DWORD src1_sel:WORD_1
	s_nop 1
	v_and_b32_e32 v0, 0xffff0000, v44
	v_or_b32_sdwa v38, v0, v38 dst_sel:DWORD dst_unused:UNUSED_PAD src0_sel:DWORD src1_sel:WORD_1
	v_mfma_f32_16x16x32_bf16 v[0:3], v[108:111], v[116:119], v[22:25]
	global_store_dwordx2 v[20:21], v[38:39], off offset:64
	v_lshlrev_b32_e32 v38, 2, v114
	v_or_b32_e32 v39, 0x11800, v38
	v_mov_b32_e32 v22, v26
	v_mov_b32_e32 v23, v28
	v_pk_mul_f32 v[22:23], v[22:23], v[54:55] op_sel_hi:[1,0]
	v_mov_b32_e32 v28, v27
	v_pk_mul_f32 v[24:25], v[28:29], v[54:55] op_sel_hi:[1,0]
	v_and_b32_sdwa v26, v23, v120 dst_sel:DWORD dst_unused:UNUSED_PAD src0_sel:WORD_1 src1_sel:DWORD
	v_and_b32_sdwa v27, v22, v120 dst_sel:DWORD dst_unused:UNUSED_PAD src0_sel:WORD_1 src1_sel:DWORD
	v_add3_u32 v23, v23, v26, s77
	v_and_b32_sdwa v26, v25, v120 dst_sel:DWORD dst_unused:UNUSED_PAD src0_sel:WORD_1 src1_sel:DWORD
	v_add3_u32 v22, v22, v27, s77
	v_and_b32_sdwa v27, v24, v120 dst_sel:DWORD dst_unused:UNUSED_PAD src0_sel:WORD_1 src1_sel:DWORD
	v_add3_u32 v25, v25, v26, s77
	v_lshlrev_b32_e32 v26, 2, v115
	v_add3_u32 v24, v24, v27, s77
	v_or_b32_e32 v27, 0x11800, v26
	v_or_b32_e32 v28, 0x11900, v26
	v_or_b32_e32 v29, 0x11a00, v26
	v_or_b32_e32 v26, 0x11b00, v26
	v_or_b32_e32 v44, 0x11900, v38
	v_or_b32_e32 v45, 0x11a00, v38
	v_or_b32_e32 v38, 0x11b00, v38
	ds_read_b32 v27, v27
	ds_read_b32 v28, v28
	ds_read_b32 v29, v29
	ds_read_b32 v26, v26
	ds_read_b32 v39, v39
	ds_read_b32 v44, v44
	ds_read_b32 v45, v45
	ds_read_b32 v38, v38
	s_waitcnt lgkmcnt(6)
	v_add_f32_e32 v27, v27, v28
	s_waitcnt lgkmcnt(5)
	v_add_f32_e32 v27, v27, v29
	s_waitcnt lgkmcnt(4)
	v_add_f32_e32 v26, v27, v26
	v_div_scale_f32 v27, s[4:5], v26, v26, 1.0
	v_rcp_f32_e32 v28, v27
	v_and_b32_e32 v25, 0xffff0000, v25
	v_and_b32_e32 v24, 0xffff0000, v24
	v_or_b32_sdwa v23, v25, v23 dst_sel:DWORD dst_unused:UNUSED_PAD src0_sel:DWORD src1_sel:WORD_1
	v_or_b32_sdwa v22, v24, v22 dst_sel:DWORD dst_unused:UNUSED_PAD src0_sel:DWORD src1_sel:WORD_1
	global_store_dwordx2 v[20:21], v[22:23], off offset:96
	v_fma_f32 v20, -v27, v28, 1.0
	v_fmac_f32_e32 v28, v20, v28
	v_div_scale_f32 v20, vcc, 1.0, v26, 1.0
	v_mfma_f32_16x16x32_bf16 v[40:43], v[8:11], v[68:71], v[144:147]
	v_mul_f32_e32 v21, v20, v28
	v_fma_f32 v22, -v27, v21, v20
	v_fmac_f32_e32 v21, v22, v28
	v_fma_f32 v20, -v27, v21, v20
	v_mfma_f32_16x16x32_bf16 v[40:43], v[172:175], v[148:151], v[40:43]
	v_div_fmas_f32 v20, v20, v28, v21
	v_div_fixup_f32 v20, v20, v26, 1.0
	v_mov_b32_e32 v24, v30
	v_mov_b32_e32 v25, v32
	v_pk_mul_f32 v[24:25], v[24:25], v[20:21] op_sel_hi:[1,0]
	v_mov_b32_e32 v32, v31
	v_pk_mul_f32 v[26:27], v[32:33], v[20:21] op_sel_hi:[1,0]
	v_and_b32_sdwa v21, v25, v120 dst_sel:DWORD dst_unused:UNUSED_PAD src0_sel:WORD_1 src1_sel:DWORD
	v_and_b32_sdwa v28, v24, v120 dst_sel:DWORD dst_unused:UNUSED_PAD src0_sel:WORD_1 src1_sel:DWORD
	v_mfma_f32_16x16x32_bf16 v[40:43], v[176:179], v[152:155], v[40:43]
	v_or_b32_e32 v22, s6, v115
	v_add3_u32 v24, v24, v28, s77
	v_add3_u32 v21, v25, v21, s77
	v_and_b32_sdwa v25, v27, v120 dst_sel:DWORD dst_unused:UNUSED_PAD src0_sel:WORD_1 src1_sel:DWORD
	v_and_b32_sdwa v28, v26, v120 dst_sel:DWORD dst_unused:UNUSED_PAD src0_sel:WORD_1 src1_sel:DWORD
	v_ashrrev_i32_e32 v23, 31, v22
	v_add3_u32 v25, v27, v25, s77
	v_add3_u32 v26, v26, v28, s77
	v_lshlrev_b64 v[22:23], 11, v[22:23]
	v_and_b32_e32 v25, 0xffff0000, v25
	v_and_b32_e32 v26, 0xffff0000, v26
	v_lshl_add_u64 v[22:23], v[52:53], 0, v[22:23]
	v_or_b32_sdwa v25, v25, v21 dst_sel:DWORD dst_unused:UNUSED_PAD src0_sel:DWORD src1_sel:WORD_1
	v_or_b32_sdwa v24, v26, v24 dst_sel:DWORD dst_unused:UNUSED_PAD src0_sel:DWORD src1_sel:WORD_1
	global_store_dwordx2 v[22:23], v[24:25], off
	v_mov_b32_e32 v24, v40
	v_mov_b32_e32 v25, v42
	v_pk_mul_f32 v[24:25], v[24:25], v[20:21] op_sel_hi:[1,0]
	v_mov_b32_e32 v42, v41
	v_pk_mul_f32 v[26:27], v[42:43], v[20:21] op_sel_hi:[1,0]
	v_and_b32_sdwa v21, v25, v120 dst_sel:DWORD dst_unused:UNUSED_PAD src0_sel:WORD_1 src1_sel:DWORD
	v_and_b32_sdwa v28, v24, v120 dst_sel:DWORD dst_unused:UNUSED_PAD src0_sel:WORD_1 src1_sel:DWORD
; __device__ __forceinline__ unsigned pack2(float a, float b) { return (unsigned)f2bf(a) | ((unsigned)f2bf(b) << 16); }
; __device__ __forceinline__ void xattn_item(const Params& p, char* smem, const int tile, const int hm) {
;     ...
; #pragma unroll
;     for (int m = 0; m < 4; ++m) {
;       const int row = m * 16 + l15;
;       const float inv = 1.f / (sSum[row] + sSum[64 + row] + sSum[128 + row] + sSum[192 + row]);
; #pragma unroll
;       for (int n = 0; n < 4; ++n)
;         *(uint2*)(xo + (size_t)(tok0 + row) * 1024 + hm * 256 + w * 64 + n * 16 + lq * 4) =
;             make_uint2(pack2(acc[m][n][0] * inv, acc[m][n][1] * inv), pack2(acc[m][n][2] * inv, acc[m][n][3] * inv));
;     }
	v_add3_u32 v24, v24, v28, s77
	v_add3_u32 v21, v25, v21, s77
	v_and_b32_sdwa v25, v27, v120 dst_sel:DWORD dst_unused:UNUSED_PAD src0_sel:WORD_1 src1_sel:DWORD
	v_and_b32_sdwa v28, v26, v120 dst_sel:DWORD dst_unused:UNUSED_PAD src0_sel:WORD_1 src1_sel:DWORD
	v_add3_u32 v25, v27, v25, s77
	v_add3_u32 v26, v26, v28, s77
	v_and_b32_e32 v25, 0xffff0000, v25
	v_and_b32_e32 v26, 0xffff0000, v26
	v_or_b32_sdwa v25, v25, v21 dst_sel:DWORD dst_unused:UNUSED_PAD src0_sel:DWORD src1_sel:WORD_1
	v_or_b32_sdwa v24, v26, v24 dst_sel:DWORD dst_unused:UNUSED_PAD src0_sel:DWORD src1_sel:WORD_1
	global_store_dwordx2 v[22:23], v[24:25], off offset:32
	v_mov_b32_e32 v24, v34
	v_mov_b32_e32 v25, v36
	v_pk_mul_f32 v[24:25], v[24:25], v[20:21] op_sel_hi:[1,0]
	v_mov_b32_e32 v36, v35
	v_pk_mul_f32 v[26:27], v[36:37], v[20:21] op_sel_hi:[1,0]
	v_and_b32_sdwa v21, v25, v120 dst_sel:DWORD dst_unused:UNUSED_PAD src0_sel:WORD_1 src1_sel:DWORD
	v_and_b32_sdwa v28, v24, v120 dst_sel:DWORD dst_unused:UNUSED_PAD src0_sel:WORD_1 src1_sel:DWORD
	v_add3_u32 v24, v24, v28, s77
	v_add3_u32 v21, v25, v21, s77
	v_and_b32_sdwa v25, v27, v120 dst_sel:DWORD dst_unused:UNUSED_PAD src0_sel:WORD_1 src1_sel:DWORD
	v_and_b32_sdwa v28, v26, v120 dst_sel:DWORD dst_unused:UNUSED_PAD src0_sel:WORD_1 src1_sel:DWORD
	v_add3_u32 v25, v27, v25, s77
	v_add3_u32 v26, v26, v28, s77
	v_and_b32_e32 v25, 0xffff0000, v25
	v_and_b32_e32 v26, 0xffff0000, v26
	v_or_b32_sdwa v25, v25, v21 dst_sel:DWORD dst_unused:UNUSED_PAD src0_sel:DWORD src1_sel:WORD_1
	v_or_b32_sdwa v24, v26, v24 dst_sel:DWORD dst_unused:UNUSED_PAD src0_sel:DWORD src1_sel:WORD_1
	global_store_dwordx2 v[22:23], v[24:25], off offset:64
	v_mov_b32_e32 v25, v18
	v_mov_b32_e32 v18, v17
	v_mov_b32_e32 v24, v16
	v_pk_mul_f32 v[16:17], v[18:19], v[20:21] op_sel_hi:[1,0]
	v_pk_mul_f32 v[24:25], v[24:25], v[20:21] op_sel_hi:[1,0]
	v_and_b32_sdwa v20, v17, v120 dst_sel:DWORD dst_unused:UNUSED_PAD src0_sel:WORD_1 src1_sel:DWORD
	v_add3_u32 v17, v17, v20, s77
	s_waitcnt lgkmcnt(2)
	v_add_f32_e32 v20, v39, v44
	s_waitcnt lgkmcnt(1)
	v_add_f32_e32 v20, v20, v45
	v_and_b32_sdwa v21, v16, v120 dst_sel:DWORD dst_unused:UNUSED_PAD src0_sel:WORD_1 src1_sel:DWORD
	s_waitcnt lgkmcnt(0)
; __device__ __forceinline__ unsigned pack2(float a, float b) { return (unsigned)f2bf(a) | ((unsigned)f2bf(b) << 16); }
; __device__ __forceinline__ void xattn_item(const Params& p, char* smem, const int tile, const int hm) {
;     ...
; #pragma unroll
;     for (int m = 0; m < 4; ++m) {
;       const int row = m * 16 + l15;
;       const float inv = 1.f / (sSum[row] + sSum[64 + row] + sSum[128 + row] + sSum[192 + row]);
; #pragma unroll
;       for (int n = 0; n < 4; ++n)
;         *(uint2*)(xo + (size_t)(tok0 + row) * 1024 + hm * 256 + w * 64 + n * 16 + lq * 4) =
;             make_uint2(pack2(acc[m][n][0] * inv, acc[m][n][1] * inv), pack2(acc[m][n][2] * inv, acc[m][n][3] * inv));
;     }
	v_add_f32_e32 v20, v20, v38
	v_mfma_f32_16x16x32_bf16 v[12:15], v[12:15], v[180:183], v[72:75]
	v_and_b32_sdwa v19, v24, v120 dst_sel:DWORD dst_unused:UNUSED_PAD src0_sel:WORD_1 src1_sel:DWORD
	v_add3_u32 v16, v16, v21, s77
	v_div_scale_f32 v21, s[4:5], v20, v20, 1.0
	v_add3_u32 v19, v24, v19, s77
	v_rcp_f32_e32 v24, v21
	v_and_b32_sdwa v18, v25, v120 dst_sel:DWORD dst_unused:UNUSED_PAD src0_sel:WORD_1 src1_sel:DWORD
	v_add3_u32 v18, v25, v18, s77
	v_and_b32_e32 v17, 0xffff0000, v17
	v_and_b32_e32 v16, 0xffff0000, v16
	v_mfma_f32_16x16x32_bf16 v[12:15], v[160:163], v[156:159], v[12:15]
	v_or_b32_sdwa v17, v17, v18 dst_sel:DWORD dst_unused:UNUSED_PAD src0_sel:DWORD src1_sel:WORD_1
	v_or_b32_sdwa v16, v16, v19 dst_sel:DWORD dst_unused:UNUSED_PAD src0_sel:DWORD src1_sel:WORD_1
	global_store_dwordx2 v[22:23], v[16:17], off offset:96
	v_fma_f32 v16, -v21, v24, 1.0
	v_fmac_f32_e32 v24, v16, v24
	v_div_scale_f32 v16, vcc, 1.0, v20, 1.0
	v_mfma_f32_16x16x32_bf16 v[8:11], v[8:11], v[180:183], v[64:67]
	v_mul_f32_e32 v17, v16, v24
	v_fma_f32 v18, -v21, v17, v16
	v_fmac_f32_e32 v17, v18, v24
	v_mfma_f32_16x16x32_bf16 v[12:15], v[164:167], v[116:119], v[12:15]
	v_fma_f32 v16, -v21, v17, v16
	v_div_fmas_f32 v16, v16, v24, v17
	v_div_fixup_f32 v16, v16, v20, 1.0
	v_mfma_f32_16x16x32_bf16 v[8:11], v[172:175], v[156:159], v[8:11]
	v_or_b32_e32 v18, s6, v114
	s_nop 2
	v_mov_b32_e32 v20, v12
	v_mov_b32_e32 v21, v14
	v_pk_mul_f32 v[20:21], v[20:21], v[16:17] op_sel_hi:[1,0]
	v_mov_b32_e32 v14, v13
	v_pk_mul_f32 v[12:13], v[14:15], v[16:17] op_sel_hi:[1,0]
	v_and_b32_sdwa v15, v20, v120 dst_sel:DWORD dst_unused:UNUSED_PAD src0_sel:WORD_1 src1_sel:DWORD
	v_mfma_f32_16x16x32_bf16 v[8:11], v[176:179], v[116:119], v[8:11]
	v_add3_u32 v15, v20, v15, s77
	v_and_b32_sdwa v17, v13, v120 dst_sel:DWORD dst_unused:UNUSED_PAD src0_sel:WORD_1 src1_sel:DWORD
	v_and_b32_sdwa v20, v12, v120 dst_sel:DWORD dst_unused:UNUSED_PAD src0_sel:WORD_1 src1_sel:DWORD
	v_ashrrev_i32_e32 v19, 31, v18
	v_and_b32_sdwa v14, v21, v120 dst_sel:DWORD dst_unused:UNUSED_PAD src0_sel:WORD_1 src1_sel:DWORD
	v_add3_u32 v13, v13, v17, s77
	v_add3_u32 v12, v12, v20, s77
	v_lshlrev_b64 v[18:19], 11, v[18:19]
	v_add3_u32 v14, v21, v14, s77
	v_and_b32_e32 v13, 0xffff0000, v13
	v_and_b32_e32 v12, 0xffff0000, v12
	v_lshl_add_u64 v[18:19], v[52:53], 0, v[18:19]
	v_or_b32_sdwa v13, v13, v14 dst_sel:DWORD dst_unused:UNUSED_PAD src0_sel:DWORD src1_sel:WORD_1
	v_or_b32_sdwa v12, v12, v15 dst_sel:DWORD dst_unused:UNUSED_PAD src0_sel:DWORD src1_sel:WORD_1
	global_store_dwordx2 v[18:19], v[12:13], off
	v_mov_b32_e32 v12, v8
	v_mov_b32_e32 v13, v10
	v_pk_mul_f32 v[12:13], v[12:13], v[16:17] op_sel_hi:[1,0]
	v_mov_b32_e32 v10, v9
	v_pk_mul_f32 v[8:9], v[10:11], v[16:17] op_sel_hi:[1,0]
	v_and_b32_sdwa v10, v13, v120 dst_sel:DWORD dst_unused:UNUSED_PAD src0_sel:WORD_1 src1_sel:DWORD
	v_and_b32_sdwa v11, v12, v120 dst_sel:DWORD dst_unused:UNUSED_PAD src0_sel:WORD_1 src1_sel:DWORD
	v_add3_u32 v11, v12, v11, s77
	v_add3_u32 v10, v13, v10, s77
	v_and_b32_sdwa v12, v9, v120 dst_sel:DWORD dst_unused:UNUSED_PAD src0_sel:WORD_1 src1_sel:DWORD
	v_and_b32_sdwa v13, v8, v120 dst_sel:DWORD dst_unused:UNUSED_PAD src0_sel:WORD_1 src1_sel:DWORD
	v_add3_u32 v9, v9, v12, s77
	v_add3_u32 v8, v8, v13, s77
	v_and_b32_e32 v9, 0xffff0000, v9
	v_and_b32_e32 v8, 0xffff0000, v8
	v_or_b32_sdwa v9, v9, v10 dst_sel:DWORD dst_unused:UNUSED_PAD src0_sel:DWORD src1_sel:WORD_1
	v_or_b32_sdwa v8, v8, v11 dst_sel:DWORD dst_unused:UNUSED_PAD src0_sel:DWORD src1_sel:WORD_1
	global_store_dwordx2 v[18:19], v[8:9], off offset:32
	v_mov_b32_e32 v8, v4
	v_mov_b32_e32 v9, v6
	v_pk_mul_f32 v[8:9], v[8:9], v[16:17] op_sel_hi:[1,0]
	v_mov_b32_e32 v6, v5
	v_pk_mul_f32 v[4:5], v[6:7], v[16:17] op_sel_hi:[1,0]
	v_and_b32_sdwa v6, v9, v120 dst_sel:DWORD dst_unused:UNUSED_PAD src0_sel:WORD_1 src1_sel:DWORD
	v_and_b32_sdwa v7, v8, v120 dst_sel:DWORD dst_unused:UNUSED_PAD src0_sel:WORD_1 src1_sel:DWORD
	v_add3_u32 v7, v8, v7, s77
	v_add3_u32 v6, v9, v6, s77
	v_and_b32_sdwa v8, v5, v120 dst_sel:DWORD dst_unused:UNUSED_PAD src0_sel:WORD_1 src1_sel:DWORD
	v_and_b32_sdwa v9, v4, v120 dst_sel:DWORD dst_unused:UNUSED_PAD src0_sel:WORD_1 src1_sel:DWORD
	v_add3_u32 v5, v5, v8, s77
	v_add3_u32 v4, v4, v9, s77
	v_and_b32_e32 v5, 0xffff0000, v5
	v_and_b32_e32 v4, 0xffff0000, v4
	v_or_b32_sdwa v5, v5, v6 dst_sel:DWORD dst_unused:UNUSED_PAD src0_sel:DWORD src1_sel:WORD_1
	v_or_b32_sdwa v4, v4, v7 dst_sel:DWORD dst_unused:UNUSED_PAD src0_sel:DWORD src1_sel:WORD_1
	global_store_dwordx2 v[18:19], v[4:5], off offset:64
	v_mov_b32_e32 v4, v0
	v_mov_b32_e32 v5, v2
	v_pk_mul_f32 v[4:5], v[4:5], v[16:17] op_sel_hi:[1,0]
	v_mov_b32_e32 v2, v1
	v_pk_mul_f32 v[0:1], v[2:3], v[16:17] op_sel_hi:[1,0]
	v_and_b32_sdwa v2, v5, v120 dst_sel:DWORD dst_unused:UNUSED_PAD src0_sel:WORD_1 src1_sel:DWORD
	v_and_b32_sdwa v3, v4, v120 dst_sel:DWORD dst_unused:UNUSED_PAD src0_sel:WORD_1 src1_sel:DWORD
	v_add3_u32 v3, v4, v3, s77
	v_add3_u32 v2, v5, v2, s77
	v_and_b32_sdwa v4, v1, v120 dst_sel:DWORD dst_unused:UNUSED_PAD src0_sel:WORD_1 src1_sel:DWORD
	v_and_b32_sdwa v5, v0, v120 dst_sel:DWORD dst_unused:UNUSED_PAD src0_sel:WORD_1 src1_sel:DWORD
	v_add3_u32 v1, v1, v4, s77
	v_add3_u32 v0, v0, v5, s77
	v_and_b32_e32 v1, 0xffff0000, v1
	v_and_b32_e32 v0, 0xffff0000, v0
	v_or_b32_sdwa v1, v1, v2 dst_sel:DWORD dst_unused:UNUSED_PAD src0_sel:DWORD src1_sel:WORD_1
	v_or_b32_sdwa v0, v0, v3 dst_sel:DWORD dst_unused:UNUSED_PAD src0_sel:DWORD src1_sel:WORD_1
	global_store_dwordx2 v[18:19], v[0:1], off offset:96
